# attention loops: S-init (-m broadcast) hoisted out of the tile loop into a persistent 16-VGPR block used as MFMA C operand; on top of GEMM vmcnt fix
# speedup vs baseline: 1.0089x; 1.0089x over previous
.LBB0_312:
	s_lshl_b32 s3, s4, 8
	s_ashr_i32 s8, s4, 4
	s_and_b32 s3, s3, 0xf00
	s_addk_i32 s4, 0xf800
	s_and_b64 s[10:11], s[0:1], exec
	s_cselect_b32 s4, s8, s4
	s_cselect_b32 s10, s3, 0
	s_ashr_i32 s8, s4, 31
	s_lshr_b32 s8, s8, 28
	s_add_i32 s8, s4, s8
	s_ashr_i32 s24, s8, 4
	s_and_b32 s8, s8, -16
	s_lshl_b32 s25, s24, 12
	s_sub_i32 s4, s4, s8
	v_add_u32_e32 v150, s10, v141
	s_addk_i32 s25, 0x2000
	s_lshl_b32 s10, s24, 8
	s_and_b64 s[0:1], s[0:1], exec
	s_cselect_b32 s0, s25, s10
	v_add_u32_e32 v0, s0, v150
	s_ashr_i32 s28, s4, 2
	s_lshl_b32 s30, s12, 1
	v_readlane_b32 s0, v243, 9
	v_readlane_b32 s1, v243, 10
	s_add_u32 s8, s0, s30
	s_addc_u32 s11, s1, 0
	s_lshl_b32 s0, s24, 2
	s_add_i32 s0, s0, s28
	s_mul_i32 s0, s0, s5
	s_ashr_i32 s1, s0, 31
	s_lshl_b64 s[36:37], s[0:1], 12
	s_add_u32 s0, s8, s36
	s_addc_u32 s1, s11, s37
	s_ashr_i32 s5, s4, 31
	s_lshl_b64 s[12:13], s[4:5], 2
	s_add_u32 s12, s88, s12
	s_addc_u32 s13, s89, s13
	v_or_b32_e32 v106, v0, v140
	global_load_dword v0, v1, s[12:13]
	s_mov_b64 s[12:13], -1
	s_and_b64 vcc, exec, s[6:7]
	v_ashrrev_i32_e32 v107, 31, v106
	s_waitcnt vmcnt(0)
	v_mul_f32_e32 v151, 0x3fb8aa3b, v0
	s_cbranch_vccz .LBB0_326
	v_mov_b32_e32 v4, v147
	v_lshlrev_b64 v[2:3], 11, v[106:107]
	s_lshl_b32 s6, s4, 6
	v_lshl_add_u64 v[2:3], s[94:95], 0, v[2:3]
	v_lshlrev_b32_e32 v0, 1, v4
	s_ashr_i32 s7, s6, 31
	v_bfe_u32 v149, v4, 5, 1
	v_and_b32_e32 v16, 8, v0
	v_lshrrev_b32_e32 v0, 1, v4
	v_lshl_add_u64 v[2:3], s[6:7], 1, v[2:3]
	s_ashr_i32 s11, s10, 31
	v_and_b32_e32 v17, 4, v0
	v_lshlrev_b32_e32 v0, 4, v149
	s_lshl_b64 s[38:39], s[10:11], 9
	v_lshl_add_u64 v[2:3], v[2:3], 0, v[0:1]
	s_add_u32 s5, s50, s38
	global_load_dwordx4 v[66:69], v[2:3], off
	global_load_dwordx4 v[70:73], v[2:3], off offset:32
	global_load_dwordx4 v[74:77], v[2:3], off offset:64
	global_load_dwordx4 v[78:81], v[2:3], off offset:96
	v_ashrrev_i32_e32 v2, 31, v4
	s_addc_u32 s8, s51, s39
	s_lshl_b32 s10, s28, 6
	v_add_u32_sdwa v2, v4, v2 dst_sel:DWORD dst_unused:UNUSED_PAD src0_sel:DWORD src1_sel:BYTE_3
	s_ashr_i32 s11, s10, 31
	v_ashrrev_i32_e32 v3, 8, v2
	v_and_b32_e32 v2, 0xffffff00, v2
	s_lshl_b64 s[40:41], s[10:11], 1
	v_ashrrev_i32_e32 v10, 3, v4
	v_sub_u32_e32 v2, v4, v2
	s_add_u32 s10, s5, s40
	v_lshlrev_b32_e32 v5, 11, v3
	v_ashrrev_i32_e32 v2, 2, v2
	v_ashrrev_i32_e32 v11, 31, v10
	s_addc_u32 s11, s8, s41
	v_and_b32_e32 v18, 19, v4
	v_and_b32_e32 v19, 3, v4
	v_and_b32_e32 v54, 31, v4
	v_lshl_add_u32 v5, v2, 5, v5
	v_lshl_add_u32 v2, v3, 6, v2
	s_movk_i32 s31, 0x50
	v_lshlrev_b64 v[52:53], 9, v[10:11]
	v_lshlrev_b32_e32 v4, 4, v4
	v_lshl_or_b32 v6, v19, 3, v5
	v_mul_lo_u32 v20, v2, s31
	v_lshl_add_u64 v[2:3], s[10:11], 0, v[52:53]
	v_and_b32_e32 v110, 0x70, v4
	v_mov_b32_e32 v111, v1
	v_lshl_add_u64 v[12:13], v[2:3], 0, v[110:111]
	v_ashrrev_i32_e32 v7, 31, v6
	s_barrier
	global_load_dwordx4 v[2:5], v[12:13], off
	v_lshlrev_b64 v[50:51], 1, v[6:7]
	v_lshl_add_u64 v[14:15], s[0:1], 0, v[50:51]
	global_load_dwordx4 v[6:9], v[14:15], off
	v_mul_lo_u32 v111, v10, s76
	v_add_u32_e32 v55, v111, v110
	s_mov_b32 s5, 0x8000
	v_lshl_add_u32 v152, v19, 4, v20
	s_movk_i32 s8, 0x2000
	s_mov_b32 s10, s9
	s_mov_b32 s11, s9
	s_mov_b32 s12, s9
	s_mov_b32 s13, s9
	s_mov_b32 s14, s9
	s_mov_b32 s15, s9
	s_mov_b32 s16, s9
	s_mov_b32 s17, s9
	s_mov_b32 s18, s9
	s_mov_b32 s19, s9
	s_mov_b32 s20, s9
	s_mov_b32 s21, s9
	s_mov_b32 s22, s9
	s_mov_b32 s23, s9
	v_lshlrev_b64 v[108:109], 10, v[106:107]
	s_mov_b32 s29, 1
	v_mad_u32_u24 v157, v54, s31, v0
	s_waitcnt vmcnt(1)
	ds_write_b128 v55, v[2:5]
	v_add_co_u32_e32 v2, vcc, s5, v12
	s_waitcnt vmcnt(0)
	ds_write_b128 v152, v[6:9] offset:9216
	v_addc_co_u32_e32 v3, vcc, 0, v13, vcc
	s_waitcnt lgkmcnt(0)
	s_barrier
	global_load_dwordx4 v[82:85], v[2:3], off
	v_add_co_u32_e32 v2, vcc, s8, v14
	s_mov_b32 s8, s9
	s_nop 0
	v_addc_co_u32_e32 v3, vcc, 0, v15, vcc
	global_load_dwordx4 v[86:89], v[2:3], off
	v_or3_b32 v2, v18, v16, v17
	v_mad_u32_u24 v153, v2, s76, v0
	ds_read_b128 v[34:37], v153 offset:4608
	ds_read_b128 v[18:21], v153
	ds_read_b128 v[38:41], v153 offset:32
	s_waitcnt lgkmcnt(1)
	v_mfma_f32_32x32x16_bf16 v[18:33], v[18:21], v[66:69], 0
	ds_read_b128 v[56:59], v153 offset:4640
	v_cmp_lt_i32_e32 vcc, v198, v200
	v_mov_b64_e32 v[2:3], s[8:9]
	v_mov_b64_e32 v[4:5], s[10:11]
	v_mov_b64_e32 v[6:7], s[12:13]
	v_mov_b64_e32 v[8:9], s[14:15]
	v_mov_b64_e32 v[10:11], s[16:17]
	s_waitcnt lgkmcnt(1)
	v_mfma_f32_32x32x16_bf16 v[18:33], v[38:41], v[70:73], v[18:33]
	ds_read_b128 v[38:41], v153 offset:64
	ds_read_b128 v[60:63], v153 offset:4672
	v_mov_b64_e32 v[12:13], s[18:19]
	v_mov_b64_e32 v[14:15], s[20:21]
	v_mov_b64_e32 v[16:17], s[22:23]
	v_readlane_b32 s8, v242, 49
	s_add_u32 s10, s8, s40
	v_readlane_b32 s8, v242, 50
	s_waitcnt lgkmcnt(1)
	v_mfma_f32_32x32x16_bf16 v[18:33], v[38:41], v[74:77], v[18:33]
	ds_read_b128 v[38:41], v153 offset:96
	ds_read_b128 v[90:93], v153 offset:4704
	s_addc_u32 s11, s8, s41
	s_add_u32 s8, s36, s30
	s_mov_b32 s5, 0
	s_waitcnt vmcnt(1)
	ds_write_b128 v55, v[82:85] offset:19456
	s_waitcnt vmcnt(0)
	ds_write_b128 v152, v[86:89] offset:28672
	s_waitcnt lgkmcnt(3)
	v_mfma_f32_32x32x16_bf16 v[18:33], v[38:41], v[78:81], v[18:33]
	s_waitcnt lgkmcnt(0)
	s_barrier
	s_nop 9
	v_max_f32_e32 v38, v19, v19
	v_max_f32_e32 v39, v18, v18
	v_max_f32_e32 v38, v39, v38
	v_max3_f32 v38, v38, v20, v21
	v_max3_f32 v38, v38, v22, v23
	v_max3_f32 v38, v38, v24, v25
	v_max3_f32 v38, v38, v26, v27
	v_max3_f32 v38, v38, v28, v29
	v_max3_f32 v38, v38, v30, v31
	v_max3_f32 v64, v38, v32, v33
	v_mfma_f32_32x32x16_bf16 v[34:49], v[34:37], v[66:69], 0
	v_mfma_f32_32x32x16_bf16 v[34:49], v[56:59], v[70:73], v[34:49]
	v_cndmask_b32_e32 v57, v197, v198, vcc
	v_lshlrev_b32_e32 v154, 2, v57
	v_mfma_f32_32x32x16_bf16 v[34:49], v[60:63], v[74:77], v[34:49]
	v_mfma_f32_32x32x16_bf16 v[34:49], v[90:93], v[78:81], v[34:49]
	s_nop 11
	v_max3_f32 v56, v64, v34, v35
	v_max3_f32 v56, v56, v36, v37
	v_max3_f32 v56, v56, v38, v39
	v_max3_f32 v56, v56, v40, v41
	v_max3_f32 v56, v56, v42, v43
	v_max3_f32 v56, v56, v44, v45
	v_max3_f32 v56, v56, v46, v47
	v_max3_f32 v56, v56, v48, v49
	ds_bpermute_b32 v57, v154, v56
	s_waitcnt lgkmcnt(0)
	v_max3_f32 v156, v151, v56, v57
	v_sub_f32_e32 v18, v18, v156
	v_exp_f32_e32 v116, v18
	v_sub_f32_e32 v18, v34, v156
	v_exp_f32_e32 v120, v18
	v_sub_f32_e32 v18, v19, v156
	v_exp_f32_e32 v117, v18
	v_sub_f32_e32 v18, v35, v156
	v_exp_f32_e32 v121, v18
	v_sub_f32_e32 v18, v20, v156
	v_exp_f32_e32 v118, v18
	v_sub_f32_e32 v18, v36, v156
	v_exp_f32_e32 v122, v18
	v_sub_f32_e32 v18, v21, v156
	v_exp_f32_e32 v119, v18
	v_sub_f32_e32 v18, v37, v156
	v_exp_f32_e32 v123, v18
	v_sub_f32_e32 v18, v22, v156
	v_exp_f32_e32 v104, v18
	v_sub_f32_e32 v18, v38, v156
	v_exp_f32_e32 v96, v18
	v_sub_f32_e32 v18, v23, v156
	v_exp_f32_e32 v105, v18
	v_sub_f32_e32 v18, v39, v156
	v_exp_f32_e32 v97, v18
	v_sub_f32_e32 v18, v24, v156
	v_exp_f32_e32 v124, v18
	v_sub_f32_e32 v18, v40, v156
	v_exp_f32_e32 v132, v18
	v_sub_f32_e32 v18, v25, v156
	v_exp_f32_e32 v125, v18
	v_sub_f32_e32 v18, v41, v156
	v_exp_f32_e32 v133, v18
	v_sub_f32_e32 v18, v26, v156
	v_exp_f32_e32 v126, v18
	v_sub_f32_e32 v18, v42, v156
	v_exp_f32_e32 v134, v18
	v_sub_f32_e32 v18, v27, v156
	v_exp_f32_e32 v127, v18
	v_sub_f32_e32 v18, v43, v156
	v_exp_f32_e32 v135, v18
	v_sub_f32_e32 v18, v28, v156
	v_exp_f32_e32 v128, v18
	v_sub_f32_e32 v18, v44, v156
	v_exp_f32_e32 v136, v18
	v_sub_f32_e32 v18, v29, v156
	v_exp_f32_e32 v129, v18
	v_sub_f32_e32 v18, v45, v156
	v_exp_f32_e32 v137, v18
	v_sub_f32_e32 v18, v30, v156
	v_exp_f32_e32 v100, v18
	v_sub_f32_e32 v18, v46, v156
	v_exp_f32_e32 v92, v18
	v_sub_f32_e32 v18, v31, v156
	v_exp_f32_e32 v101, v18
	v_sub_f32_e32 v18, v47, v156
	v_exp_f32_e32 v93, v18
	v_sub_f32_e32 v18, v32, v156
	v_exp_f32_e32 v130, v18
	v_sub_f32_e32 v18, v48, v156
	v_exp_f32_e32 v138, v18
	v_sub_f32_e32 v18, v33, v156
	v_exp_f32_e32 v131, v18
	v_sub_f32_e32 v18, v49, v156
	v_sub_f32_e32 v56, v151, v156
	v_exp_f32_e32 v139, v18
	v_lshl_add_u64 v[18:19], v[52:53], 0, s[38:39]
	v_exp_f32_e32 v56, v56
	v_or_b32_e32 v18, v18, v110
	v_lshl_add_u64 v[112:113], s[10:11], 0, v[18:19]
	s_addc_u32 s11, s37, 0
	v_readlane_b32 s10, v242, 51
	s_add_u32 s10, s10, s8
	v_readlane_b32 s8, v242, 52
	s_addc_u32 s11, s8, s11
	v_mov_b64_e32 v[32:33], v[16:17]
	v_mul_f32_e32 v155, v148, v56
	v_lshl_add_u64 v[114:115], s[10:11], 0, v[50:51]
	s_mov_b64 s[10:11], 0
	v_mov_b64_e32 v[30:31], v[14:15]
	v_mov_b64_e32 v[28:29], v[12:13]
	v_mov_b64_e32 v[26:27], v[10:11]
	v_mov_b64_e32 v[24:25], v[8:9]
	v_mov_b64_e32 v[22:23], v[6:7]
	v_mov_b64_e32 v[20:21], v[4:5]
	v_mov_b64_e32 v[18:19], v[2:3]
	v_xor_b32_e32 v220, 0x80000000, v156
	v_mov_b32_e32 v221, v220
	v_mov_b32_e32 v222, v220
	v_mov_b32_e32 v223, v220
	v_mov_b32_e32 v224, v220
	v_mov_b32_e32 v225, v220
	v_mov_b32_e32 v226, v220
	v_mov_b32_e32 v227, v220
	v_mov_b32_e32 v228, v220
	v_mov_b32_e32 v229, v220
	v_mov_b32_e32 v230, v220
	v_mov_b32_e32 v231, v220
	v_mov_b32_e32 v232, v220
	v_mov_b32_e32 v233, v220
	v_mov_b32_e32 v234, v220
	v_mov_b32_e32 v235, v220

.LBB0_316:
	s_mul_i32 s14, s8, 0x4c00
	v_add_u32_e32 v0, s14, v153
	ds_read_b128 v[158:161], v0
	ds_read_b128 v[162:165], v0 offset:4608
	ds_read_b128 v[166:169], v0 offset:32
	s_waitcnt lgkmcnt(2)
	v_mfma_f32_32x32x16_bf16 v[50:65], v[158:161], v[66:69], v[220:235]
	v_add_f32_e64 v90, v116, 0
	v_add_f32_e64 v91, v117, 0
	v_cvt_pk_bf16_f32 v102, v116, v117
	v_add_f32_e64 v90, v118, v90
	v_add_f32_e64 v91, v119, v91
	v_cvt_pk_bf16_f32 v103, v118, v119
	s_waitcnt lgkmcnt(1)
	v_mfma_f32_32x32x16_bf16 v[34:49], v[162:165], v[66:69], v[220:235]
	ds_read_b128 v[116:119], v0 offset:4640
	v_add_f32_e64 v90, v104, v90
	v_add_f32_e64 v91, v105, v91
	v_cvt_pk_bf16_f32 v104, v104, v105
	v_add_f32_e64 v90, v124, v90
	v_add_f32_e64 v91, v125, v91
	v_cvt_pk_bf16_f32 v105, v124, v125
	s_waitcnt lgkmcnt(1)
	v_mfma_f32_32x32x16_bf16 v[50:65], v[166:169], v[70:73], v[50:65]
	ds_read_b128 v[158:161], v0 offset:64
	v_add_f32_e64 v90, v126, v90
	v_add_f32_e64 v91, v127, v91
	v_cvt_pk_bf16_f32 v98, v126, v127
	v_add_f32_e64 v90, v128, v90
	v_add_f32_e64 v91, v129, v91
	v_cvt_pk_bf16_f32 v99, v128, v129
	s_waitcnt lgkmcnt(1)
	v_mfma_f32_32x32x16_bf16 v[34:49], v[116:119], v[70:73], v[34:49]
	ds_read_b128 v[124:127], v0 offset:4672
	v_add_f32_e64 v90, v100, v90
	v_add_f32_e64 v91, v101, v91
	v_cvt_pk_bf16_f32 v100, v100, v101
	v_add_f32_e64 v90, v130, v90
	v_add_f32_e64 v91, v131, v91
	v_cvt_pk_bf16_f32 v101, v130, v131
	s_waitcnt lgkmcnt(1)
	v_mfma_f32_32x32x16_bf16 v[50:65], v[158:161], v[74:77], v[50:65]
	ds_read_b128 v[116:119], v0 offset:96
	v_add_f32_e64 v90, v120, v90
	v_add_f32_e64 v91, v121, v91
	v_cvt_pk_bf16_f32 v94, v120, v121
	v_add_f32_e64 v90, v122, v90
	v_add_f32_e64 v91, v123, v91
	v_cvt_pk_bf16_f32 v95, v122, v123
	s_waitcnt lgkmcnt(1)
	v_mfma_f32_32x32x16_bf16 v[34:49], v[124:127], v[74:77], v[34:49]
	ds_read_b128 v[120:123], v0 offset:4704
	v_add_f32_e64 v90, v96, v90
	v_add_f32_e64 v91, v97, v91
	v_cvt_pk_bf16_f32 v96, v96, v97
	v_add_f32_e64 v90, v132, v90
	v_add_f32_e64 v91, v133, v91
	v_cvt_pk_bf16_f32 v97, v132, v133
	s_waitcnt lgkmcnt(1)
	v_mfma_f32_32x32x16_bf16 v[50:65], v[116:119], v[78:81], v[50:65]
	v_add_f32_e64 v116, v134, v90
	v_add_f32_e64 v117, v135, v91
	v_cvt_pk_bf16_f32 v90, v134, v135
	v_add_f32_e64 v116, v136, v116
	v_add_f32_e64 v117, v137, v117
	v_cvt_pk_bf16_f32 v91, v136, v137
	s_waitcnt lgkmcnt(0)
	v_mfma_f32_32x32x16_bf16 v[34:49], v[120:123], v[78:81], v[34:49]
	v_add_f32_e64 v116, v92, v116
	v_add_f32_e64 v117, v93, v117
	v_cvt_pk_bf16_f32 v92, v92, v93
	v_add_f32_e64 v116, v138, v116
	v_add_f32_e64 v117, v139, v117
	v_cvt_pk_bf16_f32 v93, v138, v139
	s_nop 0
	v_add_f32_e32 v0, v116, v117
	v_max_f32_e32 v116, v51, v51
	v_max_f32_e32 v117, v50, v50
	v_max_f32_e32 v116, v117, v116
	v_max3_f32 v116, v116, v52, v53
	v_max3_f32 v116, v116, v54, v55
	v_max3_f32 v116, v116, v56, v57
	v_max3_f32 v116, v116, v58, v59
	v_max3_f32 v116, v116, v60, v61
	v_max3_f32 v116, v116, v62, v63
	v_max3_f32 v116, v116, v64, v65
	v_max3_f32 v116, v116, v34, v35
	v_max3_f32 v116, v116, v36, v37
	v_max3_f32 v116, v116, v38, v39
	v_max3_f32 v116, v116, v40, v41
	v_max3_f32 v116, v116, v42, v43
	v_max3_f32 v116, v116, v44, v45
	v_max3_f32 v116, v116, v46, v47
	v_max3_f32 v116, v116, v48, v49
	v_add_f32_e32 v155, v155, v0
	ds_bpermute_b32 v0, v154, v116
	s_waitcnt lgkmcnt(0)
	v_max_f32_e32 v0, v0, v0
	v_max_f32_e32 v0, v116, v0
	v_cmp_lt_f32_e32 vcc, s33, v0
	s_cmp_lg_u64 vcc, 0
	s_cselect_b64 s[14:15], -1, 0
	s_cbranch_vccz .LBB0_318
	v_max_f32_e32 v0, v0, v0
	v_max_f32_e32 v116, 0, v0
	v_exp_f32_e64 v0, -v116
	v_add_f32_e32 v156, v156, v116
	v_xor_b32_e32 v220, 0x80000000, v156
	v_mov_b32_e32 v221, v220
	v_mov_b32_e32 v222, v220
	v_mov_b32_e32 v223, v220
	v_mov_b32_e32 v224, v220
	v_mov_b32_e32 v225, v220
	v_mov_b32_e32 v226, v220
	v_mov_b32_e32 v227, v220
	v_mov_b32_e32 v228, v220
	v_mov_b32_e32 v229, v220
	v_mov_b32_e32 v230, v220
	v_mov_b32_e32 v231, v220
	v_mov_b32_e32 v232, v220
	v_mov_b32_e32 v233, v220
	v_mov_b32_e32 v234, v220
	v_mov_b32_e32 v235, v220
	v_pk_add_f32 v[50:51], v[50:51], v[116:117] op_sel_hi:[1,0] neg_lo:[0,1] neg_hi:[0,1]
	v_pk_add_f32 v[34:35], v[34:35], v[116:117] op_sel_hi:[1,0] neg_lo:[0,1] neg_hi:[0,1]
	v_pk_add_f32 v[52:53], v[52:53], v[116:117] op_sel_hi:[1,0] neg_lo:[0,1] neg_hi:[0,1]
	v_pk_add_f32 v[36:37], v[36:37], v[116:117] op_sel_hi:[1,0] neg_lo:[0,1] neg_hi:[0,1]
	v_pk_add_f32 v[54:55], v[54:55], v[116:117] op_sel_hi:[1,0] neg_lo:[0,1] neg_hi:[0,1]
	v_pk_add_f32 v[38:39], v[38:39], v[116:117] op_sel_hi:[1,0] neg_lo:[0,1] neg_hi:[0,1]
	v_pk_add_f32 v[56:57], v[56:57], v[116:117] op_sel_hi:[1,0] neg_lo:[0,1] neg_hi:[0,1]
	v_pk_add_f32 v[40:41], v[40:41], v[116:117] op_sel_hi:[1,0] neg_lo:[0,1] neg_hi:[0,1]
	v_pk_add_f32 v[58:59], v[58:59], v[116:117] op_sel_hi:[1,0] neg_lo:[0,1] neg_hi:[0,1]
	v_pk_add_f32 v[42:43], v[42:43], v[116:117] op_sel_hi:[1,0] neg_lo:[0,1] neg_hi:[0,1]
	v_pk_add_f32 v[60:61], v[60:61], v[116:117] op_sel_hi:[1,0] neg_lo:[0,1] neg_hi:[0,1]
	v_pk_add_f32 v[44:45], v[44:45], v[116:117] op_sel_hi:[1,0] neg_lo:[0,1] neg_hi:[0,1]
	v_pk_add_f32 v[62:63], v[62:63], v[116:117] op_sel_hi:[1,0] neg_lo:[0,1] neg_hi:[0,1]
	v_pk_add_f32 v[46:47], v[46:47], v[116:117] op_sel_hi:[1,0] neg_lo:[0,1] neg_hi:[0,1]
	v_pk_add_f32 v[64:65], v[64:65], v[116:117] op_sel_hi:[1,0] neg_lo:[0,1] neg_hi:[0,1]
	v_pk_add_f32 v[48:49], v[48:49], v[116:117] op_sel_hi:[1,0] neg_lo:[0,1] neg_hi:[0,1]
	v_mul_f32_e32 v155, v155, v0
	s_branch .LBB0_319

.LBB0_326:
	s_and_b64 vcc, exec, s[12:13]
	s_cbranch_vccz .LBB0_308
	s_lshl_b32 s5, s24, 9
	s_add_i32 s6, s25, s5
	s_sub_i32 s5, 0x1080, s3
	v_mov_b32_e32 v4, v147
	s_lshr_b32 s5, s5, 6
	s_lshl_b32 s4, s4, 6
	v_lshlrev_b64 v[2:3], 11, v[106:107]
	s_min_u32 s25, s5, 10
	v_lshlrev_b32_e32 v0, 1, v4
	s_ashr_i32 s5, s4, 31
	v_lshl_add_u64 v[2:3], s[94:95], 0, v[2:3]
	v_bfe_u32 v149, v4, 5, 1
	v_and_b32_e32 v5, 8, v0
	v_lshrrev_b32_e32 v0, 1, v4
	v_lshl_add_u64 v[2:3], s[4:5], 1, v[2:3]
	v_and_b32_e32 v6, 4, v0
	v_lshlrev_b32_e32 v0, 4, v149
	s_ashr_i32 s7, s6, 31
	v_lshl_add_u64 v[2:3], v[2:3], 0, v[0:1]
	s_lshl_b64 s[6:7], s[6:7], 9
	global_load_dwordx4 v[66:69], v[2:3], off
	global_load_dwordx4 v[70:73], v[2:3], off offset:32
	global_load_dwordx4 v[74:77], v[2:3], off offset:64
	global_load_dwordx4 v[78:81], v[2:3], off offset:96
	v_ashrrev_i32_e32 v2, 31, v4
	s_add_u32 s8, s50, s6
	v_add_u32_sdwa v2, v4, v2 dst_sel:DWORD dst_unused:UNUSED_PAD src0_sel:DWORD src1_sel:BYTE_3
	s_addc_u32 s10, s51, s7
	s_lshl_b32 s6, s28, 6
	v_ashrrev_i32_e32 v3, 8, v2
	v_and_b32_e32 v2, 0xffffff00, v2
	s_ashr_i32 s7, s6, 31
	v_and_b32_e32 v7, 19, v4
	v_sub_u32_e32 v2, v4, v2
	s_lshl_b64 s[6:7], s[6:7], 1
	v_lshlrev_b64 v[108:109], 10, v[106:107]
	v_or3_b32 v13, v7, v5, v6
	v_ashrrev_i32_e32 v106, 3, v4
	v_lshlrev_b32_e32 v5, 11, v3
	v_ashrrev_i32_e32 v2, 2, v2
	s_add_u32 s6, s8, s6
	v_lshl_add_u32 v5, v2, 5, v5
	v_lshl_add_u32 v2, v3, 6, v2
	s_movk_i32 s31, 0x50
	v_ashrrev_i32_e32 v107, 31, v106
	s_addc_u32 s7, s10, s7
	v_and_b32_e32 v12, 3, v4
	v_and_b32_e32 v50, 31, v4
	v_mul_lo_u32 v14, v2, s31
	v_lshlrev_b64 v[2:3], 9, v[106:107]
	v_lshlrev_b32_e32 v4, 4, v4
	v_lshl_add_u64 v[2:3], s[6:7], 0, v[2:3]
	v_and_b32_e32 v110, 0x70, v4
	v_mov_b32_e32 v111, v1
	v_lshl_or_b32 v6, v12, 3, v5
	v_lshl_add_u64 v[10:11], v[2:3], 0, v[110:111]
	s_waitcnt lgkmcnt(0)
	s_barrier
	global_load_dwordx4 v[2:5], v[10:11], off
	v_ashrrev_i32_e32 v7, 31, v6
	v_lshl_add_u64 v[112:113], v[6:7], 1, s[0:1]
	global_load_dwordx4 v[6:9], v[112:113], off
	v_mul_lo_u32 v107, v106, s76
	v_add_u32_e32 v51, v107, v110
	s_mov_b32 s0, 0x8000
	v_lshl_add_u32 v152, v12, 4, v14
	v_mad_u32_u24 v153, v13, s76, v0
	s_cmp_eq_u32 s3, 0
	s_cselect_b32 s8, 6, 8
	s_cselect_b32 s30, 0x80, 0
	s_add_i32 s25, s25, s8
	s_mov_b32 s8, s9
	s_mov_b32 s10, s9
	s_mov_b32 s11, s9
	s_mov_b32 s12, s9
	s_mov_b32 s13, s9
	s_mov_b32 s14, s9
	s_mov_b32 s15, s9
	s_mov_b32 s16, s9
	s_mov_b32 s17, s9
	s_mov_b32 s18, s9
	s_mov_b32 s19, s9
	s_mov_b32 s20, s9
	s_mov_b32 s21, s9
	s_mov_b32 s22, s9
	s_mov_b32 s23, s9
	s_add_i32 s3, s30, s3
	v_lshl_add_u64 v[114:115], s[6:7], 0, v[110:111]
	v_mad_u32_u24 v111, v50, s31, v0
	v_lshl_add_u32 v0, v149, 3, s3
	s_mov_b32 s29, 1
	s_mov_b32 s28, 0
	s_movk_i32 s24, 0x80
	s_mov_b32 s6, 1
	s_waitcnt vmcnt(1)
	ds_write_b128 v51, v[2:5]
	v_add_co_u32_e32 v2, vcc, s0, v10
	s_movk_i32 s0, 0x2000
	s_nop 0
	v_addc_co_u32_e32 v3, vcc, 0, v11, vcc
	s_waitcnt vmcnt(0)
	ds_write_b128 v152, v[6:9] offset:9216
	s_waitcnt lgkmcnt(0)
	s_barrier
	global_load_dwordx4 v[82:85], v[2:3], off
	v_add_co_u32_e32 v2, vcc, s0, v112
	ds_read_b128 v[34:37], v153 offset:4608
	s_nop 0
	v_addc_co_u32_e32 v3, vcc, 0, v113, vcc
	global_load_dwordx4 v[86:89], v[2:3], off
	ds_read_b128 v[18:21], v153
	ds_read_b128 v[38:41], v153 offset:32
	s_waitcnt lgkmcnt(1)
	v_mfma_f32_32x32x16_bf16 v[18:33], v[18:21], v[66:69], 0
	ds_read_b128 v[52:55], v153 offset:4640
	v_cmp_lt_i32_e32 vcc, v198, v200
	v_mov_b64_e32 v[2:3], s[8:9]
	v_mov_b64_e32 v[16:17], s[22:23]
	v_mov_b64_e32 v[4:5], s[10:11]
	v_mov_b64_e32 v[6:7], s[12:13]
	v_mov_b64_e32 v[8:9], s[14:15]
	s_waitcnt lgkmcnt(1)
	v_mfma_f32_32x32x16_bf16 v[18:33], v[38:41], v[70:73], v[18:33]
	ds_read_b128 v[38:41], v153 offset:64
	ds_read_b128 v[56:59], v153 offset:4672
	v_mov_b64_e32 v[10:11], s[16:17]
	v_mov_b64_e32 v[12:13], s[18:19]
	v_mov_b64_e32 v[14:15], s[20:21]
	s_movk_i32 s14, 0x101
	s_waitcnt lgkmcnt(1)
	v_mfma_f32_32x32x16_bf16 v[18:33], v[38:41], v[74:77], v[18:33]
	ds_read_b128 v[38:41], v153 offset:96
	ds_read_b128 v[60:63], v153 offset:4704
	s_waitcnt vmcnt(1)
	ds_write_b128 v51, v[82:85] offset:19456
	s_waitcnt vmcnt(0)
	ds_write_b128 v152, v[86:89] offset:28672
	s_waitcnt lgkmcnt(3)
	v_mfma_f32_32x32x16_bf16 v[18:33], v[38:41], v[78:81], v[18:33]
	s_waitcnt lgkmcnt(0)
	s_barrier
	s_nop 9
	v_max_f32_e32 v38, v19, v19
	v_max_f32_e32 v39, v18, v18
	v_max_f32_e32 v38, v39, v38
	v_max3_f32 v38, v38, v20, v21
	v_max3_f32 v38, v38, v22, v23
	v_max3_f32 v38, v38, v24, v25
	v_max3_f32 v38, v38, v26, v27
	v_max3_f32 v38, v38, v28, v29
	v_max3_f32 v38, v38, v30, v31
	v_max3_f32 v64, v38, v32, v33
	v_mfma_f32_32x32x16_bf16 v[34:49], v[34:37], v[66:69], 0
	v_mfma_f32_32x32x16_bf16 v[34:49], v[52:55], v[70:73], v[34:49]
	v_cndmask_b32_e32 v53, v197, v198, vcc
	v_lshlrev_b32_e32 v154, 2, v53
	v_mfma_f32_32x32x16_bf16 v[34:49], v[56:59], v[74:77], v[34:49]
	v_mfma_f32_32x32x16_bf16 v[34:49], v[60:63], v[78:81], v[34:49]
	s_nop 11
	v_max3_f32 v52, v64, v34, v35
	v_max3_f32 v52, v52, v36, v37
	v_max3_f32 v52, v52, v38, v39
	v_max3_f32 v52, v52, v40, v41
	v_max3_f32 v52, v52, v42, v43
	v_max3_f32 v52, v52, v44, v45
	v_max3_f32 v52, v52, v46, v47
	v_max3_f32 v52, v52, v48, v49
	ds_bpermute_b32 v53, v154, v52
	s_waitcnt lgkmcnt(0)
	v_max3_f32 v155, v151, v52, v53
	v_sub_f32_e32 v18, v18, v155
	v_exp_f32_e32 v116, v18
	v_sub_f32_e32 v18, v34, v155
	v_exp_f32_e32 v120, v18
	v_sub_f32_e32 v18, v19, v155
	v_exp_f32_e32 v117, v18
	v_sub_f32_e32 v18, v35, v155
	v_exp_f32_e32 v121, v18
	v_sub_f32_e32 v18, v20, v155
	v_exp_f32_e32 v118, v18
	v_sub_f32_e32 v18, v36, v155
	v_exp_f32_e32 v128, v18
	v_sub_f32_e32 v18, v21, v155
	v_exp_f32_e32 v119, v18
	v_sub_f32_e32 v18, v37, v155
	v_exp_f32_e32 v129, v18
	v_sub_f32_e32 v18, v22, v155
	v_exp_f32_e32 v104, v18
	v_sub_f32_e32 v18, v38, v155
	v_exp_f32_e32 v96, v18
	v_sub_f32_e32 v18, v23, v155
	v_exp_f32_e32 v105, v18
	v_sub_f32_e32 v18, v39, v155
	v_exp_f32_e32 v97, v18
	v_sub_f32_e32 v18, v24, v155
	v_exp_f32_e32 v122, v18
	v_sub_f32_e32 v18, v40, v155
	v_exp_f32_e32 v132, v18
	v_sub_f32_e32 v18, v25, v155
	v_exp_f32_e32 v123, v18
	v_sub_f32_e32 v18, v41, v155
	v_exp_f32_e32 v133, v18
	v_sub_f32_e32 v18, v26, v155
	v_exp_f32_e32 v124, v18
	v_sub_f32_e32 v18, v42, v155
	v_exp_f32_e32 v134, v18
	v_sub_f32_e32 v18, v27, v155
	v_exp_f32_e32 v125, v18
	v_sub_f32_e32 v18, v43, v155
	v_exp_f32_e32 v135, v18
	v_sub_f32_e32 v18, v28, v155
	v_exp_f32_e32 v126, v18
	v_sub_f32_e32 v18, v44, v155
	v_exp_f32_e32 v136, v18
	v_sub_f32_e32 v18, v29, v155
	v_exp_f32_e32 v127, v18
	v_sub_f32_e32 v18, v45, v155
	v_exp_f32_e32 v137, v18
	v_sub_f32_e32 v18, v30, v155
	v_exp_f32_e32 v100, v18
	v_sub_f32_e32 v18, v46, v155
	v_exp_f32_e32 v92, v18
	v_sub_f32_e32 v18, v31, v155
	v_exp_f32_e32 v101, v18
	v_sub_f32_e32 v18, v47, v155
	v_exp_f32_e32 v93, v18
	v_sub_f32_e32 v18, v32, v155
	v_exp_f32_e32 v130, v18
	v_sub_f32_e32 v18, v48, v155
	v_sub_f32_e32 v52, v151, v155
	v_exp_f32_e32 v138, v18
	v_sub_f32_e32 v18, v33, v155
	v_exp_f32_e32 v52, v52
	v_exp_f32_e32 v131, v18
	v_sub_f32_e32 v18, v49, v155
	v_exp_f32_e32 v139, v18
	v_add_u32_e32 v18, v150, v50
	v_sub_u32_e32 v150, v0, v18
	v_mov_b64_e32 v[32:33], v[16:17]
	v_mul_f32_e32 v151, v148, v52
	v_mov_b64_e32 v[30:31], v[14:15]
	v_mov_b64_e32 v[28:29], v[12:13]
	v_mov_b64_e32 v[26:27], v[10:11]
	v_mov_b64_e32 v[24:25], v[8:9]
	v_mov_b64_e32 v[22:23], v[6:7]
	v_mov_b64_e32 v[20:21], v[4:5]
	v_mov_b64_e32 v[18:19], v[2:3]
	v_xor_b32_e32 v220, 0x80000000, v155
	v_mov_b32_e32 v221, v220
	v_mov_b32_e32 v222, v220
	v_mov_b32_e32 v223, v220
	v_mov_b32_e32 v224, v220
	v_mov_b32_e32 v225, v220
	v_mov_b32_e32 v226, v220
	v_mov_b32_e32 v227, v220
	v_mov_b32_e32 v228, v220
	v_mov_b32_e32 v229, v220
	v_mov_b32_e32 v230, v220
	v_mov_b32_e32 v231, v220
	v_mov_b32_e32 v232, v220
	v_mov_b32_e32 v233, v220
	v_mov_b32_e32 v234, v220
	v_mov_b32_e32 v235, v220

.LBB0_330:
	s_mul_i32 s11, s8, 0x4c00
	v_add_u32_e32 v0, s11, v153
	ds_read_b128 v[156:159], v0
	ds_read_b128 v[160:163], v0 offset:4608
	ds_read_b128 v[164:167], v0 offset:32
	s_waitcnt lgkmcnt(2)
	v_mfma_f32_32x32x16_bf16 v[50:65], v[156:159], v[66:69], v[220:235]
	v_add_f32_e64 v90, v116, 0
	v_add_f32_e64 v91, v117, 0
	v_cvt_pk_bf16_f32 v102, v116, v117
	v_add_f32_e64 v90, v118, v90
	v_add_f32_e64 v91, v119, v91
	v_cvt_pk_bf16_f32 v103, v118, v119
	s_waitcnt lgkmcnt(1)
	v_mfma_f32_32x32x16_bf16 v[34:49], v[160:163], v[66:69], v[220:235]
	ds_read_b128 v[116:119], v0 offset:4640
	v_add_f32_e64 v90, v104, v90
	v_add_f32_e64 v91, v105, v91
	v_cvt_pk_bf16_f32 v104, v104, v105
	v_add_f32_e64 v90, v122, v90
	v_add_f32_e64 v91, v123, v91
	v_cvt_pk_bf16_f32 v105, v122, v123
	s_waitcnt lgkmcnt(1)
	v_mfma_f32_32x32x16_bf16 v[50:65], v[164:167], v[70:73], v[50:65]
	ds_read_b128 v[156:159], v0 offset:64
	v_add_f32_e64 v90, v124, v90
	v_add_f32_e64 v91, v125, v91
	v_cvt_pk_bf16_f32 v98, v124, v125
	v_add_f32_e64 v90, v126, v90
	v_add_f32_e64 v91, v127, v91
	v_cvt_pk_bf16_f32 v99, v126, v127
	s_waitcnt lgkmcnt(1)
	v_mfma_f32_32x32x16_bf16 v[34:49], v[116:119], v[70:73], v[34:49]
	ds_read_b128 v[122:125], v0 offset:4672
	v_add_f32_e64 v90, v100, v90
	v_add_f32_e64 v91, v101, v91
	v_cvt_pk_bf16_f32 v100, v100, v101
	v_add_f32_e64 v90, v130, v90
	v_add_f32_e64 v91, v131, v91
	v_cvt_pk_bf16_f32 v101, v130, v131
	s_waitcnt lgkmcnt(1)
	v_mfma_f32_32x32x16_bf16 v[50:65], v[156:159], v[74:77], v[50:65]
	ds_read_b128 v[116:119], v0 offset:96
	v_add_f32_e64 v90, v120, v90
	v_add_f32_e64 v91, v121, v91
	v_cvt_pk_bf16_f32 v94, v120, v121
	v_add_f32_e64 v90, v128, v90
	v_add_f32_e64 v91, v129, v91
	v_cvt_pk_bf16_f32 v95, v128, v129
	s_waitcnt lgkmcnt(1)
	v_mfma_f32_32x32x16_bf16 v[34:49], v[122:125], v[74:77], v[34:49]
	ds_read_b128 v[126:129], v0 offset:4704
	v_add_f32_e64 v90, v96, v90
	v_add_f32_e64 v91, v97, v91
	v_cvt_pk_bf16_f32 v96, v96, v97
	v_add_f32_e64 v90, v132, v90
	v_add_f32_e64 v91, v133, v91
	v_cvt_pk_bf16_f32 v97, v132, v133
	s_waitcnt lgkmcnt(1)
	v_mfma_f32_32x32x16_bf16 v[50:65], v[116:119], v[78:81], v[50:65]
	v_add_f32_e64 v116, v134, v90
	v_add_f32_e64 v117, v135, v91
	v_cvt_pk_bf16_f32 v90, v134, v135
	v_add_f32_e64 v116, v136, v116
	v_add_f32_e64 v117, v137, v117
	v_cvt_pk_bf16_f32 v91, v136, v137
	s_waitcnt lgkmcnt(0)
	v_mfma_f32_32x32x16_bf16 v[34:49], v[126:129], v[78:81], v[34:49]
	v_add_f32_e64 v116, v92, v116
	v_add_f32_e64 v117, v93, v117
	v_cvt_pk_bf16_f32 v92, v92, v93
	v_add_f32_e64 v116, v138, v116
	v_add_f32_e64 v117, v139, v117
	v_cvt_pk_bf16_f32 v93, v138, v139
	s_cmp_lt_u32 s6, 8
	s_cbranch_scc1 .LBB0_332
	v_add_u32_e32 v0, s24, v150
	v_add_u32_e32 v118, 0xfffffdc0, v0
	v_cmp_gt_u32_e32 vcc, s14, v118
	v_add_u32_e32 v118, 0xfffffdc1, v0
	s_nop 0
	v_cndmask_b32_e32 v50, v201, v50, vcc
	v_cmp_gt_u32_e32 vcc, s14, v118
	v_add_u32_e32 v118, 0xfffffdc2, v0
	s_nop 0
	v_cndmask_b32_e32 v51, v201, v51, vcc
	v_cmp_gt_u32_e32 vcc, s14, v118
	v_add_u32_e32 v118, 0xfffffdc3, v0
	s_nop 0
	v_cndmask_b32_e32 v52, v201, v52, vcc
	v_cmp_gt_u32_e32 vcc, s14, v118
	v_add_u32_e32 v118, 0xfffffdc4, v0
	s_nop 0
	v_cndmask_b32_e32 v53, v201, v53, vcc
	v_cmp_gt_u32_e32 vcc, s14, v118
	v_add_u32_e32 v118, 0xfffffdc5, v0
	s_nop 0
	v_cndmask_b32_e32 v54, v201, v54, vcc
	v_cmp_gt_u32_e32 vcc, s14, v118
	v_add_u32_e32 v118, 0xfffffdc6, v0
	s_nop 0
	v_cndmask_b32_e32 v55, v201, v55, vcc
	v_cmp_gt_u32_e32 vcc, s14, v118
	v_add_u32_e32 v118, 0xfffffdc7, v0
	s_nop 0
	v_cndmask_b32_e32 v56, v201, v56, vcc
	v_cmp_gt_u32_e32 vcc, s14, v118
	v_add_u32_e32 v118, 0xfffffdd0, v0
	s_nop 0
	v_cndmask_b32_e32 v57, v201, v57, vcc
	v_cmp_gt_u32_e32 vcc, s14, v118
	v_add_u32_e32 v118, 0xfffffdd1, v0
	s_nop 0
	v_cndmask_b32_e32 v58, v201, v58, vcc
	v_cmp_gt_u32_e32 vcc, s14, v118
	v_add_u32_e32 v118, 0xfffffdd2, v0
	s_nop 0
	v_cndmask_b32_e32 v59, v201, v59, vcc
	v_cmp_gt_u32_e32 vcc, s14, v118
	v_add_u32_e32 v118, 0xfffffdd3, v0
	s_nop 0
	v_cndmask_b32_e32 v60, v201, v60, vcc
	v_cmp_gt_u32_e32 vcc, s14, v118
	v_add_u32_e32 v118, 0xfffffdd4, v0
	s_nop 0
	v_cndmask_b32_e32 v61, v201, v61, vcc
	v_cmp_gt_u32_e32 vcc, s14, v118
	v_add_u32_e32 v118, 0xfffffdd5, v0
	s_nop 0
	v_cndmask_b32_e32 v62, v201, v62, vcc
	v_cmp_gt_u32_e32 vcc, s14, v118
	v_add_u32_e32 v118, 0xfffffdd6, v0
	s_nop 0
	v_cndmask_b32_e32 v63, v201, v63, vcc
	v_cmp_gt_u32_e32 vcc, s14, v118
	v_add_u32_e32 v118, 0xfffffdd7, v0
	s_nop 0
	v_cndmask_b32_e32 v64, v201, v64, vcc
	v_cmp_gt_u32_e32 vcc, s14, v118
	v_add_u32_e32 v118, 0xfffffde0, v0
	s_nop 0
	v_cndmask_b32_e32 v65, v201, v65, vcc
	v_cmp_gt_u32_e32 vcc, s14, v118
	v_add_u32_e32 v118, 0xfffffde1, v0
	s_nop 0
	v_cndmask_b32_e32 v34, v201, v34, vcc
	v_cmp_gt_u32_e32 vcc, s14, v118
	v_add_u32_e32 v118, 0xfffffde2, v0
	s_nop 0
	v_cndmask_b32_e32 v35, v201, v35, vcc
	v_cmp_gt_u32_e32 vcc, s14, v118
	v_add_u32_e32 v118, 0xfffffde3, v0
	s_nop 0
	v_cndmask_b32_e32 v36, v201, v36, vcc
	v_cmp_gt_u32_e32 vcc, s14, v118
	v_add_u32_e32 v118, 0xfffffde4, v0
	s_nop 0
	v_cndmask_b32_e32 v37, v201, v37, vcc
	v_cmp_gt_u32_e32 vcc, s14, v118
	v_add_u32_e32 v118, 0xfffffde5, v0
	s_nop 0
	v_cndmask_b32_e32 v38, v201, v38, vcc
	v_cmp_gt_u32_e32 vcc, s14, v118
	v_add_u32_e32 v118, 0xfffffde6, v0
	s_nop 0
	v_cndmask_b32_e32 v39, v201, v39, vcc
	v_cmp_gt_u32_e32 vcc, s14, v118
	v_add_u32_e32 v118, 0xfffffde7, v0
	s_nop 0
	v_cndmask_b32_e32 v40, v201, v40, vcc
	v_cmp_gt_u32_e32 vcc, s14, v118
	v_add_u32_e32 v118, 0xfffffdf0, v0
	s_nop 0
	v_cndmask_b32_e32 v41, v201, v41, vcc
	v_cmp_gt_u32_e32 vcc, s14, v118
	v_add_u32_e32 v118, 0xfffffdf1, v0
	s_nop 0
	v_cndmask_b32_e32 v42, v201, v42, vcc
	v_cmp_gt_u32_e32 vcc, s14, v118
	v_add_u32_e32 v118, 0xfffffdf2, v0
	s_nop 0
	v_cndmask_b32_e32 v43, v201, v43, vcc
	v_cmp_gt_u32_e32 vcc, s14, v118
	v_add_u32_e32 v118, 0xfffffdf3, v0
	s_nop 0
	v_cndmask_b32_e32 v44, v201, v44, vcc
	v_cmp_gt_u32_e32 vcc, s14, v118
	v_add_u32_e32 v118, 0xfffffdf4, v0
	s_nop 0
	v_cndmask_b32_e32 v45, v201, v45, vcc
	v_cmp_gt_u32_e32 vcc, s14, v118
	v_add_u32_e32 v118, 0xfffffdf5, v0
	s_nop 0
	v_cndmask_b32_e32 v46, v201, v46, vcc
	v_cmp_gt_u32_e32 vcc, s14, v118
	v_add_u32_e32 v118, 0xfffffdf6, v0
	v_add_u32_e32 v0, 0xfffffdf7, v0
	v_cndmask_b32_e32 v47, v201, v47, vcc
	v_cmp_gt_u32_e32 vcc, s14, v118
	s_nop 1
	v_cndmask_b32_e32 v48, v201, v48, vcc
	v_cmp_gt_u32_e32 vcc, s14, v0
	s_nop 1
	v_cndmask_b32_e32 v49, v201, v49, vcc
.LBB0_332:
	v_add_f32_e32 v0, v116, v117
	v_add_f32_e32 v151, v151, v0
	v_max_f32_e32 v0, v51, v51
	v_max_f32_e32 v116, v50, v50
	v_max_f32_e32 v0, v116, v0
	v_max3_f32 v0, v0, v52, v53
	v_max3_f32 v0, v0, v54, v55
	v_max3_f32 v0, v0, v56, v57
	v_max3_f32 v0, v0, v58, v59
	v_max3_f32 v0, v0, v60, v61
	v_max3_f32 v0, v0, v62, v63
	v_max3_f32 v0, v0, v64, v65
	v_max3_f32 v0, v0, v34, v35
	v_max3_f32 v0, v0, v36, v37
	v_max3_f32 v0, v0, v38, v39
	v_max3_f32 v0, v0, v40, v41
	v_max3_f32 v0, v0, v42, v43
	v_max3_f32 v0, v0, v44, v45
	v_max3_f32 v0, v0, v46, v47
	v_max3_f32 v0, v0, v48, v49
	ds_bpermute_b32 v116, v154, v0
	s_waitcnt lgkmcnt(0)
	v_max_f32_e32 v116, v116, v116
	v_max_f32_e32 v0, v0, v116
	v_cmp_lt_f32_e32 vcc, s33, v0
	s_cmp_lg_u64 vcc, 0
	s_cselect_b64 s[6:7], -1, 0
	s_cbranch_vccz .LBB0_334
	v_max_f32_e32 v0, v0, v0
	v_max_f32_e32 v116, 0, v0
	v_exp_f32_e64 v0, -v116
	v_add_f32_e32 v155, v155, v116
	v_xor_b32_e32 v220, 0x80000000, v155
	v_mov_b32_e32 v221, v220
	v_mov_b32_e32 v222, v220
	v_mov_b32_e32 v223, v220
	v_mov_b32_e32 v224, v220
	v_mov_b32_e32 v225, v220
	v_mov_b32_e32 v226, v220
	v_mov_b32_e32 v227, v220
	v_mov_b32_e32 v228, v220
	v_mov_b32_e32 v229, v220
	v_mov_b32_e32 v230, v220
	v_mov_b32_e32 v231, v220
	v_mov_b32_e32 v232, v220
	v_mov_b32_e32 v233, v220
	v_mov_b32_e32 v234, v220
	v_mov_b32_e32 v235, v220
	v_pk_add_f32 v[50:51], v[50:51], v[116:117] op_sel_hi:[1,0] neg_lo:[0,1] neg_hi:[0,1]
	v_pk_add_f32 v[34:35], v[34:35], v[116:117] op_sel_hi:[1,0] neg_lo:[0,1] neg_hi:[0,1]
	v_pk_add_f32 v[52:53], v[52:53], v[116:117] op_sel_hi:[1,0] neg_lo:[0,1] neg_hi:[0,1]
	v_pk_add_f32 v[36:37], v[36:37], v[116:117] op_sel_hi:[1,0] neg_lo:[0,1] neg_hi:[0,1]
	v_pk_add_f32 v[54:55], v[54:55], v[116:117] op_sel_hi:[1,0] neg_lo:[0,1] neg_hi:[0,1]
	v_pk_add_f32 v[38:39], v[38:39], v[116:117] op_sel_hi:[1,0] neg_lo:[0,1] neg_hi:[0,1]
	v_pk_add_f32 v[56:57], v[56:57], v[116:117] op_sel_hi:[1,0] neg_lo:[0,1] neg_hi:[0,1]
	v_pk_add_f32 v[40:41], v[40:41], v[116:117] op_sel_hi:[1,0] neg_lo:[0,1] neg_hi:[0,1]
	v_pk_add_f32 v[58:59], v[58:59], v[116:117] op_sel_hi:[1,0] neg_lo:[0,1] neg_hi:[0,1]
	v_pk_add_f32 v[42:43], v[42:43], v[116:117] op_sel_hi:[1,0] neg_lo:[0,1] neg_hi:[0,1]
	v_pk_add_f32 v[60:61], v[60:61], v[116:117] op_sel_hi:[1,0] neg_lo:[0,1] neg_hi:[0,1]
	v_pk_add_f32 v[44:45], v[44:45], v[116:117] op_sel_hi:[1,0] neg_lo:[0,1] neg_hi:[0,1]
	v_pk_add_f32 v[62:63], v[62:63], v[116:117] op_sel_hi:[1,0] neg_lo:[0,1] neg_hi:[0,1]
	v_pk_add_f32 v[46:47], v[46:47], v[116:117] op_sel_hi:[1,0] neg_lo:[0,1] neg_hi:[0,1]
	v_pk_add_f32 v[64:65], v[64:65], v[116:117] op_sel_hi:[1,0] neg_lo:[0,1] neg_hi:[0,1]
	v_pk_add_f32 v[48:49], v[48:49], v[116:117] op_sel_hi:[1,0] neg_lo:[0,1] neg_hi:[0,1]
	v_mul_f32_e32 v151, v151, v0
	s_branch .LBB0_335

.LBB0_355:
	s_or_b64 exec, exec, s[14:15]
	v_lshlrev_b32_e32 v2, 1, v42
	v_lshrrev_b32_e32 v3, 1, v42
	v_and_b32_e32 v2, 8, v2
	v_and_b32_e32 v3, 4, v3
	v_and_b32_e32 v4, 19, v42
	v_or3_b32 v2, v4, v2, v3
	v_mul_u32_u24_e32 v2, 0xd0, v2
	v_add_u32_e32 v173, v2, v0
	ds_read_b128 v[2:5], v173
	ds_read_b128 v[18:21], v173 offset:32
	s_waitcnt lgkmcnt(1)
	v_mfma_f32_32x32x16_bf16 v[2:17], v[2:5], v[66:69], 0
	v_add_co_u32_e32 v40, vcc, 0x2000, v40
	s_movk_i32 s8, 0xd0
	s_nop 0
	v_addc_co_u32_e32 v41, vcc, 0, v41, vcc
	v_cmp_lt_i32_e32 vcc, v198, v200
	v_mul_lo_u32 v175, v36, s8
	s_waitcnt lgkmcnt(0)
	v_mfma_f32_32x32x16_bf16 v[2:17], v[18:21], v[70:73], v[2:17]
	ds_read_b128 v[18:21], v173 offset:64
	ds_read_b128 v[22:25], v173 offset:96
	s_waitcnt lgkmcnt(1)
	v_mfma_f32_32x32x16_bf16 v[2:17], v[18:21], v[74:77], v[2:17]
	s_waitcnt lgkmcnt(0)
	v_mfma_f32_32x32x16_bf16 v[2:17], v[22:25], v[78:81], v[2:17]
	ds_read_b128 v[18:21], v173 offset:128
	ds_read_b128 v[22:25], v173 offset:160
	s_waitcnt lgkmcnt(1)
	v_mfma_f32_32x32x16_bf16 v[2:17], v[18:21], v[82:85], v[2:17]
	ds_read_b128 v[18:21], v173 offset:6656
	ds_read_b128 v[44:47], v173 offset:6688
	global_load_dwordx4 v[98:101], v[40:41], off
	ds_read_b128 v[48:51], v173 offset:6752
	s_waitcnt lgkmcnt(3)
	v_mfma_f32_32x32x16_bf16 v[2:17], v[22:25], v[86:89], v[2:17]
	s_waitcnt lgkmcnt(2)
	v_mfma_f32_32x32x16_bf16 v[18:33], v[18:21], v[66:69], 0
	s_nop 9
	v_max_f32_e32 v40, v3, v3
	v_max_f32_e32 v41, v2, v2
	v_max_f32_e32 v40, v41, v40
	v_max3_f32 v40, v40, v4, v5
	v_max3_f32 v40, v40, v6, v7
	v_max3_f32 v40, v40, v8, v9
	v_max3_f32 v40, v40, v10, v11
	s_waitcnt lgkmcnt(1)
	v_mfma_f32_32x32x16_bf16 v[18:33], v[44:47], v[70:73], v[18:33]
	ds_read_b128 v[44:47], v173 offset:6720
	v_max3_f32 v40, v40, v12, v13
	v_max3_f32 v40, v40, v14, v15
	v_max3_f32 v40, v40, v16, v17
	v_cndmask_b32_e32 v41, v197, v198, vcc
	v_lshlrev_b32_e32 v125, 2, v41
	s_waitcnt lgkmcnt(0)
	v_mfma_f32_32x32x16_bf16 v[18:33], v[44:47], v[74:77], v[18:33]
	v_mfma_f32_32x32x16_bf16 v[18:33], v[48:51], v[78:81], v[18:33]
	ds_read_b128 v[44:47], v173 offset:6784
	ds_read_b128 v[48:51], v173 offset:6816
	s_waitcnt vmcnt(1)
	ds_write_b128 v43, v[94:97] offset:23552
	s_waitcnt lgkmcnt(2)
	v_mfma_f32_32x32x16_bf16 v[18:33], v[44:47], v[82:85], v[18:33]
	s_waitcnt lgkmcnt(1)
	v_mfma_f32_32x32x16_bf16 v[18:33], v[48:51], v[86:89], v[18:33]
	s_nop 11
	v_max3_f32 v40, v40, v18, v19
	v_max3_f32 v40, v40, v20, v21
	v_max3_f32 v40, v40, v22, v23
	v_max3_f32 v40, v40, v24, v25
	v_max3_f32 v40, v40, v26, v27
	v_max3_f32 v40, v40, v28, v29
	v_max3_f32 v40, v40, v30, v31
	v_max3_f32 v40, v40, v32, v33
	ds_bpermute_b32 v41, v125, v40
	s_and_saveexec_b64 s[14:15], s[0:1]
	v_add_u32_e32 v43, v175, v122
	ds_write_b128 v43, v[90:93] offset:23680
	s_or_b64 exec, exec, s[14:15]
	s_mov_b32 s8, 0xf149f2ca
	s_waitcnt lgkmcnt(0)
	v_max3_f32 v176, v40, v41, s8
	v_sub_f32_e32 v2, v2, v176
	v_exp_f32_e32 v136, v2
	v_sub_f32_e32 v2, v18, v176
	v_exp_f32_e32 v148, v2
	v_sub_f32_e32 v2, v3, v176
	v_exp_f32_e32 v137, v2
	v_sub_f32_e32 v2, v19, v176
	v_exp_f32_e32 v149, v2
	v_sub_f32_e32 v2, v4, v176
	v_exp_f32_e32 v134, v2
	v_sub_f32_e32 v2, v20, v176
	v_exp_f32_e32 v140, v2
	v_sub_f32_e32 v2, v5, v176
	v_exp_f32_e32 v135, v2
	v_sub_f32_e32 v2, v21, v176
	v_exp_f32_e32 v141, v2
	v_sub_f32_e32 v2, v6, v176
	v_exp_f32_e32 v132, v2
	v_sub_f32_e32 v2, v22, v176
	v_exp_f32_e32 v154, v2
	v_sub_f32_e32 v2, v7, v176
	v_exp_f32_e32 v133, v2
	v_sub_f32_e32 v2, v23, v176
	v_exp_f32_e32 v155, v2
	v_sub_f32_e32 v2, v8, v176
	v_exp_f32_e32 v138, v2
	v_sub_f32_e32 v2, v24, v176
	v_exp_f32_e32 v158, v2
	v_sub_f32_e32 v2, v9, v176
	v_exp_f32_e32 v139, v2
	v_sub_f32_e32 v2, v25, v176
	v_exp_f32_e32 v159, v2
	v_sub_f32_e32 v2, v10, v176
	v_exp_f32_e32 v152, v2
	v_sub_f32_e32 v2, v26, v176
	v_exp_f32_e32 v162, v2
	v_sub_f32_e32 v2, v11, v176
	v_exp_f32_e32 v153, v2
	v_sub_f32_e32 v2, v27, v176
	v_exp_f32_e32 v163, v2
	v_sub_f32_e32 v2, v12, v176
	v_exp_f32_e32 v150, v2
	v_sub_f32_e32 v2, v28, v176
	v_exp_f32_e32 v164, v2
	v_sub_f32_e32 v2, v13, v176
	v_exp_f32_e32 v151, v2
	v_sub_f32_e32 v2, v29, v176
	v_exp_f32_e32 v165, v2
	v_sub_f32_e32 v2, v14, v176
	v_exp_f32_e32 v156, v2
	v_sub_f32_e32 v2, v30, v176
	v_exp_f32_e32 v166, v2
	v_sub_f32_e32 v2, v15, v176
	v_exp_f32_e32 v157, v2
	v_sub_f32_e32 v2, v31, v176
	v_sub_f32_e32 v3, 0xf149f2ca, v176
	v_exp_f32_e32 v167, v2
	v_sub_f32_e32 v2, v16, v176
	v_exp_f32_e32 v3, v3
	v_exp_f32_e32 v160, v2
	v_sub_f32_e32 v2, v32, v176
	v_exp_f32_e32 v168, v2
	v_sub_f32_e32 v2, v17, v176
	v_exp_f32_e32 v161, v2
	v_sub_f32_e32 v2, v33, v176
	v_exp_f32_e32 v169, v2
	v_mul_f32_e32 v174, 0, v3
	v_lshlrev_b64 v[2:3], 6, v[36:37]
	v_lshl_add_u64 v[2:3], v[2:3], 0, s[10:11]
	v_mov_b32_e32 v123, v1
	v_lshl_add_u64 v[126:127], v[2:3], 0, v[122:123]
	v_lshl_add_u64 v[2:3], v[34:35], 0, s[6:7]
	v_mov_b32_e32 v121, v1
	v_lshl_add_u64 v[2:3], v[2:3], 0, v[120:121]
	v_lshl_add_u64 v[2:3], s[4:5], 1, v[2:3]
	s_mov_b64 s[6:7], 0x7840000
	v_and_b32_e32 v42, 31, v42
	v_lshl_add_u64 v[128:129], v[2:3], 0, s[6:7]
	s_add_u32 s6, s12, s20
	v_mul_u32_u24_e32 v42, 0x50, v42
	s_addc_u32 s7, s13, 0
	v_mov_b32_e32 v14, v1
	v_mov_b32_e32 v15, v1
	v_add_u32_e32 v177, v42, v0
	s_add_u32 s6, s6, 0xd004000
	v_mov_b32_e32 v0, v1
	v_mov_b32_e32 v2, v1
	v_mov_b32_e32 v3, v1
	v_mov_b32_e32 v4, v1
	v_mov_b32_e32 v5, v1
	v_mov_b32_e32 v6, v1
	v_mov_b32_e32 v7, v1
	v_mov_b32_e32 v8, v1
	v_mov_b32_e32 v9, v1
	v_mov_b32_e32 v10, v1
	v_mov_b32_e32 v11, v1
	v_mov_b32_e32 v12, v1
	v_mov_b32_e32 v13, v1
	v_mov_b64_e32 v[32:33], v[14:15]
	s_addc_u32 s7, s7, 0
	v_mov_b64_e32 v[30:31], v[12:13]
	v_mov_b64_e32 v[28:29], v[10:11]
	v_mov_b64_e32 v[26:27], v[8:9]
	v_mov_b64_e32 v[24:25], v[6:7]
	v_mov_b64_e32 v[22:23], v[4:5]
	v_mov_b64_e32 v[20:21], v[2:3]
	v_mov_b64_e32 v[18:19], v[0:1]
	v_mov_b64_e32 v[16:17], v[14:15]
	v_ashrrev_i32_e32 v119, 31, v118
	s_mov_b32 s8, 1
	v_lshl_add_u64 v[130:131], v[38:39], 1, s[6:7]
	s_mov_b32 s14, 0
	v_mov_b64_e32 v[14:15], v[12:13]
	v_mov_b64_e32 v[12:13], v[10:11]
	v_mov_b64_e32 v[10:11], v[8:9]
	v_mov_b64_e32 v[8:9], v[6:7]
	v_mov_b64_e32 v[6:7], v[4:5]
	v_mov_b64_e32 v[4:5], v[2:3]
	v_mov_b64_e32 v[2:3], v[0:1]
	s_mov_b32 s12, 1
	s_waitcnt vmcnt(0)
	ds_write_b128 v124, v[98:101] offset:36864
	s_waitcnt lgkmcnt(0)
	s_barrier
	v_xor_b32_e32 v220, 0x80000000, v176
	v_mov_b32_e32 v221, v220
	v_mov_b32_e32 v222, v220
	v_mov_b32_e32 v223, v220
	v_mov_b32_e32 v224, v220
	v_mov_b32_e32 v225, v220
	v_mov_b32_e32 v226, v220
	v_mov_b32_e32 v227, v220
	v_mov_b32_e32 v228, v220
	v_mov_b32_e32 v229, v220
	v_mov_b32_e32 v230, v220
	v_mov_b32_e32 v231, v220
	v_mov_b32_e32 v232, v220
	v_mov_b32_e32 v233, v220
	v_mov_b32_e32 v234, v220
	v_mov_b32_e32 v235, v220

.LBB0_362:
	s_mul_i32 s13, s12, 0x5c00
	v_add_u32_e32 v0, s13, v173
	ds_read_b128 v[102:105], v0
	ds_read_b128 v[106:109], v0 offset:6656
	ds_read_b128 v[110:113], v0 offset:32
	s_waitcnt lgkmcnt(2)
	v_mfma_f32_32x32x16_bf16 v[50:65], v[102:105], v[66:69], v[220:235]
	v_cvt_pk_bf16_f32 v114, v136, v137
	v_add_f32_e64 v116, v136, 0
	v_add_f32_e64 v117, v137, 0
	s_waitcnt lgkmcnt(1)
	v_mfma_f32_32x32x16_bf16 v[34:49], v[106:109], v[66:69], v[220:235]
	ds_read_b128 v[102:105], v0 offset:6688
	v_cvt_pk_bf16_f32 v115, v134, v135
	v_add_f32_e64 v134, v134, v116
	v_add_f32_e64 v135, v135, v117
	s_waitcnt lgkmcnt(1)
	v_mfma_f32_32x32x16_bf16 v[50:65], v[110:113], v[70:73], v[50:65]
	ds_read_b128 v[106:109], v0 offset:64
	v_add_f32_e64 v110, v132, v134
	v_add_f32_e64 v111, v133, v135
	v_cvt_pk_bf16_f32 v116, v132, v133
	v_cvt_pk_bf16_f32 v117, v138, v139
	v_pk_add_f32 v[112:113], v[138:139], v[110:111]
	s_nop 0
	s_waitcnt lgkmcnt(1)
	v_mfma_f32_32x32x16_bf16 v[34:49], v[102:105], v[70:73], v[34:49]
	ds_read_b128 v[132:135], v0 offset:6720
	v_cvt_pk_bf16_f32 v110, v152, v153
	v_add_f32_e64 v112, v152, v112
	v_add_f32_e64 v113, v153, v113
	s_waitcnt lgkmcnt(1)
	v_mfma_f32_32x32x16_bf16 v[50:65], v[106:109], v[74:77], v[50:65]
	ds_read_b128 v[102:105], v0 offset:96
	v_cvt_pk_bf16_f32 v111, v150, v151
	v_add_f32_e64 v106, v150, v112
	v_add_f32_e64 v107, v151, v113
	s_waitcnt lgkmcnt(1)
	v_mfma_f32_32x32x16_bf16 v[34:49], v[132:135], v[74:77], v[34:49]
	ds_read_b128 v[136:139], v0 offset:6752
	v_add_f32_e64 v106, v156, v106
	v_add_f32_e64 v107, v157, v107
	v_cvt_pk_bf16_f32 v112, v156, v157
	v_cvt_pk_bf16_f32 v113, v160, v161
	v_pk_add_f32 v[108:109], v[160:161], v[106:107]
	s_nop 0
	s_waitcnt lgkmcnt(1)
	v_mfma_f32_32x32x16_bf16 v[50:65], v[102:105], v[78:81], v[50:65]
	ds_read_b128 v[132:135], v0 offset:128
	v_cvt_pk_bf16_f32 v106, v148, v149
	v_add_f32_e64 v108, v148, v108
	v_add_f32_e64 v109, v149, v109
	s_waitcnt lgkmcnt(1)
	v_mfma_f32_32x32x16_bf16 v[34:49], v[136:139], v[78:81], v[34:49]
	ds_read_b128 v[102:105], v0 offset:6784
	v_cvt_pk_bf16_f32 v107, v140, v141
	v_add_f32_e64 v140, v140, v108
	v_add_f32_e64 v141, v141, v109
	s_waitcnt lgkmcnt(1)
	v_mfma_f32_32x32x16_bf16 v[50:65], v[132:135], v[82:85], v[50:65]
	ds_read_b128 v[136:139], v0 offset:160
	v_add_f32_e64 v132, v154, v140
	v_add_f32_e64 v133, v155, v141
	v_cvt_pk_bf16_f32 v108, v154, v155
	v_cvt_pk_bf16_f32 v109, v158, v159
	v_pk_add_f32 v[140:141], v[158:159], v[132:133]
	s_nop 0
	s_waitcnt lgkmcnt(1)
	v_mfma_f32_32x32x16_bf16 v[34:49], v[102:105], v[82:85], v[34:49]
	ds_read_b128 v[132:135], v0 offset:6816
	v_cvt_pk_bf16_f32 v102, v162, v163
	v_add_f32_e64 v104, v162, v140
	v_add_f32_e64 v105, v163, v141
	s_waitcnt lgkmcnt(1)
	v_mfma_f32_32x32x16_bf16 v[50:65], v[136:139], v[86:89], v[50:65]
	v_cvt_pk_bf16_f32 v103, v164, v165
	v_add_f32_e64 v136, v164, v104
	v_add_f32_e64 v137, v165, v105
	s_waitcnt lgkmcnt(0)
	v_mfma_f32_32x32x16_bf16 v[34:49], v[132:135], v[86:89], v[34:49]
	v_add_f32_e64 v132, v166, v136
	v_add_f32_e64 v133, v167, v137
	v_cvt_pk_bf16_f32 v104, v166, v167
	v_cvt_pk_bf16_f32 v105, v168, v169
	v_add_f32_e64 v132, v168, v132
	v_add_f32_e64 v133, v169, v133
	s_nop 0
	v_max_f32_e32 v121, v51, v51
	v_max_f32_e32 v123, v50, v50
	v_max_f32_e32 v121, v123, v121
	v_max3_f32 v121, v121, v52, v53
	v_max3_f32 v121, v121, v54, v55
	v_max3_f32 v121, v121, v56, v57
	v_max3_f32 v121, v121, v58, v59
	v_max3_f32 v121, v121, v60, v61
	v_max3_f32 v121, v121, v62, v63
	v_max3_f32 v121, v121, v64, v65
	v_max3_f32 v121, v121, v34, v35
	v_max3_f32 v121, v121, v36, v37
	v_max3_f32 v121, v121, v38, v39
	v_max3_f32 v121, v121, v40, v41
	v_max3_f32 v121, v121, v42, v43
	v_max3_f32 v121, v121, v44, v45
	v_max3_f32 v121, v121, v46, v47
	v_add_f32_e32 v0, v132, v133
	v_max3_f32 v121, v121, v48, v49
	v_add_f32_e32 v174, v174, v0
	ds_bpermute_b32 v0, v125, v121
	s_waitcnt lgkmcnt(0)
	v_max_f32_e32 v0, v0, v0
	v_max_f32_e32 v0, v121, v0
	v_cmp_lt_f32_e32 vcc, s33, v0
	s_cmp_lg_u64 vcc, 0
	s_cselect_b64 s[10:11], -1, 0
	s_cbranch_vccz .LBB0_364
	v_max_f32_e32 v0, v0, v0
	v_max_f32_e32 v132, 0, v0
	v_exp_f32_e64 v0, -v132
	v_add_f32_e32 v176, v176, v132
	v_xor_b32_e32 v220, 0x80000000, v176
	v_mov_b32_e32 v221, v220
	v_mov_b32_e32 v222, v220
	v_mov_b32_e32 v223, v220
	v_mov_b32_e32 v224, v220
	v_mov_b32_e32 v225, v220
	v_mov_b32_e32 v226, v220
	v_mov_b32_e32 v227, v220
	v_mov_b32_e32 v228, v220
	v_mov_b32_e32 v229, v220
	v_mov_b32_e32 v230, v220
	v_mov_b32_e32 v231, v220
	v_mov_b32_e32 v232, v220
	v_mov_b32_e32 v233, v220
	v_mov_b32_e32 v234, v220
	v_mov_b32_e32 v235, v220
	v_pk_add_f32 v[50:51], v[50:51], v[132:133] op_sel_hi:[1,0] neg_lo:[0,1] neg_hi:[0,1]
	v_pk_add_f32 v[34:35], v[34:35], v[132:133] op_sel_hi:[1,0] neg_lo:[0,1] neg_hi:[0,1]
	v_pk_add_f32 v[52:53], v[52:53], v[132:133] op_sel_hi:[1,0] neg_lo:[0,1] neg_hi:[0,1]
	v_pk_add_f32 v[36:37], v[36:37], v[132:133] op_sel_hi:[1,0] neg_lo:[0,1] neg_hi:[0,1]
	v_pk_add_f32 v[54:55], v[54:55], v[132:133] op_sel_hi:[1,0] neg_lo:[0,1] neg_hi:[0,1]
	v_pk_add_f32 v[38:39], v[38:39], v[132:133] op_sel_hi:[1,0] neg_lo:[0,1] neg_hi:[0,1]
	v_pk_add_f32 v[56:57], v[56:57], v[132:133] op_sel_hi:[1,0] neg_lo:[0,1] neg_hi:[0,1]
	v_pk_add_f32 v[40:41], v[40:41], v[132:133] op_sel_hi:[1,0] neg_lo:[0,1] neg_hi:[0,1]
	v_pk_add_f32 v[58:59], v[58:59], v[132:133] op_sel_hi:[1,0] neg_lo:[0,1] neg_hi:[0,1]
	v_pk_add_f32 v[42:43], v[42:43], v[132:133] op_sel_hi:[1,0] neg_lo:[0,1] neg_hi:[0,1]
	v_pk_add_f32 v[60:61], v[60:61], v[132:133] op_sel_hi:[1,0] neg_lo:[0,1] neg_hi:[0,1]
	v_pk_add_f32 v[44:45], v[44:45], v[132:133] op_sel_hi:[1,0] neg_lo:[0,1] neg_hi:[0,1]
	v_pk_add_f32 v[62:63], v[62:63], v[132:133] op_sel_hi:[1,0] neg_lo:[0,1] neg_hi:[0,1]
	v_pk_add_f32 v[46:47], v[46:47], v[132:133] op_sel_hi:[1,0] neg_lo:[0,1] neg_hi:[0,1]
	v_pk_add_f32 v[64:65], v[64:65], v[132:133] op_sel_hi:[1,0] neg_lo:[0,1] neg_hi:[0,1]
	v_pk_add_f32 v[48:49], v[48:49], v[132:133] op_sel_hi:[1,0] neg_lo:[0,1] neg_hi:[0,1]
	v_mul_f32_e32 v174, v174, v0
	s_branch .LBB0_365

.LBB0_391:
	s_lshl_b32 s8, s8, 4
	s_sub_i32 s24, s5, s8
	s_lshl_b32 s28, s0, 1
	v_readlane_b32 s10, v243, 9
	v_readlane_b32 s11, v243, 10
	s_add_u32 s8, s10, s28
	s_mul_i32 s0, s1, s5
	s_addc_u32 s10, s11, 0
	s_ashr_i32 s1, s0, 31
	s_lshl_b64 s[36:37], s[0:1], 12
	v_or_b32_e32 v106, v0, v140
	s_add_u32 s0, s8, s36
	s_addc_u32 s1, s10, s37
	s_mov_b64 s[10:11], -1
	s_and_b64 vcc, exec, s[6:7]
	v_ashrrev_i32_e32 v107, 31, v106
	s_cbranch_vccz .LBB0_405
	s_lshl_b32 s6, s24, 6
	v_mov_b32_e32 v4, v147
	v_lshlrev_b64 v[2:3], 11, v[106:107]
	s_ashr_i32 s7, s6, 31
	v_lshl_add_u64 v[2:3], s[94:95], 0, v[2:3]
	v_lshlrev_b32_e32 v0, 1, v4
	s_lshl_b64 s[38:39], s[6:7], 1
	v_bfe_u32 v153, v4, 5, 1
	v_and_b32_e32 v16, 8, v0
	v_lshrrev_b32_e32 v0, 1, v4
	v_lshl_add_u64 v[2:3], v[2:3], 0, s[38:39]
	v_and_b32_e32 v17, 4, v0
	v_lshlrev_b32_e32 v0, 4, v153
	v_lshl_add_u64 v[2:3], v[2:3], 0, v[0:1]
	s_ashr_i32 s5, s4, 31
	global_load_dwordx4 v[66:69], v[2:3], off
	global_load_dwordx4 v[70:73], v[2:3], off offset:32
	global_load_dwordx4 v[74:77], v[2:3], off offset:64
	global_load_dwordx4 v[78:81], v[2:3], off offset:96
	v_ashrrev_i32_e32 v2, 31, v4
	s_lshl_b64 s[40:41], s[4:5], 11
	v_add_u32_sdwa v2, v4, v2 dst_sel:DWORD dst_unused:UNUSED_PAD src0_sel:DWORD src1_sel:BYTE_3
	s_add_u32 s5, s50, s40
	v_ashrrev_i32_e32 v3, 8, v2
	v_and_b32_e32 v2, 0xffffff00, v2
	s_addc_u32 s8, s51, s41
	v_ashrrev_i32_e32 v10, 3, v4
	v_sub_u32_e32 v2, v4, v2
	s_add_u32 s10, s5, s38
	v_lshlrev_b32_e32 v5, 11, v3
	v_ashrrev_i32_e32 v2, 2, v2
	v_ashrrev_i32_e32 v11, 31, v10
	s_addc_u32 s11, s8, s39
	v_and_b32_e32 v18, 19, v4
	v_and_b32_e32 v19, 3, v4
	v_and_b32_e32 v54, 31, v4
	v_lshl_add_u32 v5, v2, 5, v5
	v_lshl_add_u32 v2, v3, 6, v2
	s_movk_i32 s29, 0x50
	v_lshlrev_b64 v[52:53], 11, v[10:11]
	v_lshlrev_b32_e32 v4, 4, v4
	v_lshl_or_b32 v6, v19, 3, v5
	v_mul_lo_u32 v20, v2, s29
	v_lshl_add_u64 v[2:3], s[10:11], 0, v[52:53]
	v_and_b32_e32 v110, 0x70, v4
	v_mov_b32_e32 v111, v1
	v_lshl_add_u64 v[12:13], v[2:3], 0, v[110:111]
	v_ashrrev_i32_e32 v7, 31, v6
	s_barrier
	global_load_dwordx4 v[2:5], v[12:13], off
	v_lshlrev_b64 v[50:51], 1, v[6:7]
	v_lshl_add_u64 v[14:15], s[0:1], 0, v[50:51]
	global_load_dwordx4 v[6:9], v[14:15], off
	v_mul_lo_u32 v111, v10, s76
	v_add_u32_e32 v55, v111, v110
	s_mov_b32 s5, 0x20000
	v_lshl_add_u32 v154, v19, 4, v20
	s_movk_i32 s8, 0x2000
	s_mov_b32 s10, s9
	s_mov_b32 s11, s9
	s_mov_b32 s12, s9
	s_mov_b32 s13, s9
	s_mov_b32 s14, s9
	s_mov_b32 s15, s9
	s_mov_b32 s16, s9
	s_mov_b32 s17, s9
	s_mov_b32 s18, s9
	s_mov_b32 s19, s9
	s_mov_b32 s20, s9
	s_mov_b32 s21, s9
	s_mov_b32 s22, s9
	s_mov_b32 s23, s9
	v_lshlrev_b64 v[108:109], 10, v[106:107]
	s_mov_b32 s25, 1
	v_mad_u32_u24 v159, v54, s29, v0
	s_waitcnt vmcnt(1)
	ds_write_b128 v55, v[2:5]
	v_add_co_u32_e32 v2, vcc, s5, v12
	s_waitcnt vmcnt(0)
	ds_write_b128 v154, v[6:9] offset:9216
	v_addc_co_u32_e32 v3, vcc, 0, v13, vcc
	s_waitcnt lgkmcnt(0)
	s_barrier
	global_load_dwordx4 v[82:85], v[2:3], off
	v_add_co_u32_e32 v2, vcc, s8, v14
	s_mov_b32 s8, s9
	s_nop 0
	v_addc_co_u32_e32 v3, vcc, 0, v15, vcc
	global_load_dwordx4 v[86:89], v[2:3], off
	v_or3_b32 v2, v18, v16, v17
	v_mad_u32_u24 v155, v2, s76, v0
	ds_read_b128 v[34:37], v155 offset:4608
	ds_read_b128 v[18:21], v155
	ds_read_b128 v[38:41], v155 offset:32
	s_waitcnt lgkmcnt(1)
	v_mfma_f32_32x32x16_bf16 v[18:33], v[18:21], v[66:69], 0
	ds_read_b128 v[56:59], v155 offset:4640
	v_cmp_lt_i32_e32 vcc, v198, v200
	v_mov_b64_e32 v[2:3], s[8:9]
	v_mov_b64_e32 v[4:5], s[10:11]
	v_mov_b64_e32 v[6:7], s[12:13]
	v_mov_b64_e32 v[8:9], s[14:15]
	v_mov_b64_e32 v[10:11], s[16:17]
	s_waitcnt lgkmcnt(1)
	v_mfma_f32_32x32x16_bf16 v[18:33], v[38:41], v[70:73], v[18:33]
	ds_read_b128 v[38:41], v155 offset:64
	ds_read_b128 v[60:63], v155 offset:4672
	v_mov_b64_e32 v[12:13], s[18:19]
	v_mov_b64_e32 v[14:15], s[20:21]
	v_mov_b64_e32 v[16:17], s[22:23]
	s_mov_b32 s8, 0xf149f2ca
	s_mov_b32 s5, 0
	s_waitcnt lgkmcnt(1)
	v_mfma_f32_32x32x16_bf16 v[18:33], v[38:41], v[74:77], v[18:33]
	ds_read_b128 v[38:41], v155 offset:96
	ds_read_b128 v[90:93], v155 offset:4704
	s_waitcnt vmcnt(1)
	ds_write_b128 v55, v[82:85] offset:19456
	s_waitcnt vmcnt(0)
	ds_write_b128 v154, v[86:89] offset:28672
	s_waitcnt lgkmcnt(3)
	v_mfma_f32_32x32x16_bf16 v[18:33], v[38:41], v[78:81], v[18:33]
	s_waitcnt lgkmcnt(0)
	s_barrier
	s_nop 9
	v_max_f32_e32 v38, v19, v19
	v_max_f32_e32 v39, v18, v18
	v_max_f32_e32 v38, v39, v38
	v_max3_f32 v38, v38, v20, v21
	v_max3_f32 v38, v38, v22, v23
	v_max3_f32 v38, v38, v24, v25
	v_max3_f32 v38, v38, v26, v27
	v_max3_f32 v38, v38, v28, v29
	v_max3_f32 v38, v38, v30, v31
	v_max3_f32 v64, v38, v32, v33
	v_mfma_f32_32x32x16_bf16 v[34:49], v[34:37], v[66:69], 0
	v_mfma_f32_32x32x16_bf16 v[34:49], v[56:59], v[70:73], v[34:49]
	v_cndmask_b32_e32 v57, v197, v198, vcc
	v_lshlrev_b32_e32 v156, 2, v57
	v_mfma_f32_32x32x16_bf16 v[34:49], v[60:63], v[74:77], v[34:49]
	v_mfma_f32_32x32x16_bf16 v[34:49], v[90:93], v[78:81], v[34:49]
	s_nop 11
	v_max3_f32 v56, v64, v34, v35
	v_max3_f32 v56, v56, v36, v37
	v_max3_f32 v56, v56, v38, v39
	v_max3_f32 v56, v56, v40, v41
	v_max3_f32 v56, v56, v42, v43
	v_max3_f32 v56, v56, v44, v45
	v_max3_f32 v56, v56, v46, v47
	v_max3_f32 v56, v56, v48, v49
	ds_bpermute_b32 v57, v156, v56
	s_waitcnt lgkmcnt(0)
	v_max3_f32 v158, v56, v57, s8
	v_sub_f32_e32 v18, v18, v158
	v_exp_f32_e32 v116, v18
	v_sub_f32_e32 v18, v34, v158
	v_exp_f32_e32 v120, v18
	v_sub_f32_e32 v18, v19, v158
	v_exp_f32_e32 v117, v18
	v_sub_f32_e32 v18, v35, v158
	v_exp_f32_e32 v121, v18
	v_sub_f32_e32 v18, v20, v158
	v_exp_f32_e32 v118, v18
	v_sub_f32_e32 v18, v36, v158
	v_exp_f32_e32 v122, v18
	v_sub_f32_e32 v18, v21, v158
	v_exp_f32_e32 v119, v18
	v_sub_f32_e32 v18, v37, v158
	v_exp_f32_e32 v123, v18
	v_sub_f32_e32 v18, v22, v158
	v_exp_f32_e32 v104, v18
	v_sub_f32_e32 v18, v38, v158
	v_exp_f32_e32 v96, v18
	v_sub_f32_e32 v18, v23, v158
	v_exp_f32_e32 v105, v18
	v_sub_f32_e32 v18, v39, v158
	v_exp_f32_e32 v97, v18
	v_sub_f32_e32 v18, v24, v158
	v_exp_f32_e32 v124, v18
	v_sub_f32_e32 v18, v40, v158
	v_exp_f32_e32 v132, v18
	v_sub_f32_e32 v18, v25, v158
	v_exp_f32_e32 v125, v18
	v_sub_f32_e32 v18, v41, v158
	v_exp_f32_e32 v133, v18
	v_sub_f32_e32 v18, v26, v158
	v_exp_f32_e32 v126, v18
	v_sub_f32_e32 v18, v42, v158
	v_exp_f32_e32 v134, v18
	v_sub_f32_e32 v18, v27, v158
	v_exp_f32_e32 v127, v18
	v_sub_f32_e32 v18, v43, v158
	v_exp_f32_e32 v135, v18
	v_sub_f32_e32 v18, v28, v158
	v_exp_f32_e32 v128, v18
	v_sub_f32_e32 v18, v44, v158
	v_exp_f32_e32 v136, v18
	v_sub_f32_e32 v18, v29, v158
	v_exp_f32_e32 v129, v18
	v_sub_f32_e32 v18, v45, v158
	v_exp_f32_e32 v137, v18
	v_sub_f32_e32 v18, v30, v158
	v_exp_f32_e32 v100, v18
	v_sub_f32_e32 v18, v46, v158
	v_exp_f32_e32 v92, v18
	v_sub_f32_e32 v18, v31, v158
	v_exp_f32_e32 v101, v18
	v_sub_f32_e32 v18, v47, v158
	v_exp_f32_e32 v93, v18
	v_sub_f32_e32 v18, v32, v158
	v_exp_f32_e32 v130, v18
	v_sub_f32_e32 v18, v48, v158
	v_exp_f32_e32 v138, v18
	v_sub_f32_e32 v18, v33, v158
	v_readlane_b32 s8, v242, 53
	v_exp_f32_e32 v131, v18
	v_sub_f32_e32 v18, v49, v158
	s_add_u32 s10, s8, s38
	v_readlane_b32 s8, v242, 54
	v_sub_f32_e32 v56, 0xf149f2ca, v158
	v_exp_f32_e32 v139, v18
	v_lshl_add_u64 v[18:19], s[40:41], 0, v[52:53]
	s_addc_u32 s11, s8, s39
	v_exp_f32_e32 v56, v56
	v_or_b32_e32 v18, v18, v110
	s_add_u32 s8, s36, s28
	v_lshl_add_u64 v[112:113], s[10:11], 0, v[18:19]
	s_addc_u32 s11, s37, 0
	v_readlane_b32 s10, v242, 51
	s_add_u32 s10, s10, s8
	v_readlane_b32 s8, v242, 52
	s_addc_u32 s11, s8, s11
	v_mov_b64_e32 v[32:33], v[16:17]
	v_mul_f32_e32 v157, 0, v56
	v_lshl_add_u64 v[114:115], s[10:11], 0, v[50:51]
	s_mov_b64 s[10:11], 0
	v_mov_b64_e32 v[30:31], v[14:15]
	v_mov_b64_e32 v[28:29], v[12:13]
	v_mov_b64_e32 v[26:27], v[10:11]
	v_mov_b64_e32 v[24:25], v[8:9]
	v_mov_b64_e32 v[22:23], v[6:7]
	v_mov_b64_e32 v[20:21], v[4:5]
	v_mov_b64_e32 v[18:19], v[2:3]
	v_xor_b32_e32 v220, 0x80000000, v158
	v_mov_b32_e32 v221, v220
	v_mov_b32_e32 v222, v220
	v_mov_b32_e32 v223, v220
	v_mov_b32_e32 v224, v220
	v_mov_b32_e32 v225, v220
	v_mov_b32_e32 v226, v220
	v_mov_b32_e32 v227, v220
	v_mov_b32_e32 v228, v220
	v_mov_b32_e32 v229, v220
	v_mov_b32_e32 v230, v220
	v_mov_b32_e32 v231, v220
	v_mov_b32_e32 v232, v220
	v_mov_b32_e32 v233, v220
	v_mov_b32_e32 v234, v220
	v_mov_b32_e32 v235, v220

.LBB0_395:
	s_mul_i32 s14, s8, 0x4c00
	v_add_u32_e32 v0, s14, v155
	ds_read_b128 v[160:163], v0
	ds_read_b128 v[164:167], v0 offset:4608
	ds_read_b128 v[168:171], v0 offset:32
	s_waitcnt lgkmcnt(2)
	v_mfma_f32_32x32x16_bf16 v[50:65], v[160:163], v[66:69], v[220:235]
	v_add_f32_e64 v90, v116, 0
	v_add_f32_e64 v91, v117, 0
	v_cvt_pk_bf16_f32 v102, v116, v117
	v_add_f32_e64 v90, v118, v90
	v_add_f32_e64 v91, v119, v91
	v_cvt_pk_bf16_f32 v103, v118, v119
	s_waitcnt lgkmcnt(1)
	v_mfma_f32_32x32x16_bf16 v[34:49], v[164:167], v[66:69], v[220:235]
	ds_read_b128 v[116:119], v0 offset:4640
	v_add_f32_e64 v90, v104, v90
	v_add_f32_e64 v91, v105, v91
	v_cvt_pk_bf16_f32 v104, v104, v105
	v_add_f32_e64 v90, v124, v90
	v_add_f32_e64 v91, v125, v91
	v_cvt_pk_bf16_f32 v105, v124, v125
	s_waitcnt lgkmcnt(1)
	v_mfma_f32_32x32x16_bf16 v[50:65], v[168:171], v[70:73], v[50:65]
	ds_read_b128 v[160:163], v0 offset:64
	v_add_f32_e64 v90, v126, v90
	v_add_f32_e64 v91, v127, v91
	v_cvt_pk_bf16_f32 v98, v126, v127
	v_add_f32_e64 v90, v128, v90
	v_add_f32_e64 v91, v129, v91
	v_cvt_pk_bf16_f32 v99, v128, v129
	s_waitcnt lgkmcnt(1)
	v_mfma_f32_32x32x16_bf16 v[34:49], v[116:119], v[70:73], v[34:49]
	ds_read_b128 v[124:127], v0 offset:4672
	v_add_f32_e64 v90, v100, v90
	v_add_f32_e64 v91, v101, v91
	v_cvt_pk_bf16_f32 v100, v100, v101
	v_add_f32_e64 v90, v130, v90
	v_add_f32_e64 v91, v131, v91
	v_cvt_pk_bf16_f32 v101, v130, v131
	s_waitcnt lgkmcnt(1)
	v_mfma_f32_32x32x16_bf16 v[50:65], v[160:163], v[74:77], v[50:65]
	ds_read_b128 v[116:119], v0 offset:96
	v_add_f32_e64 v90, v120, v90
	v_add_f32_e64 v91, v121, v91
	v_cvt_pk_bf16_f32 v94, v120, v121
	v_add_f32_e64 v90, v122, v90
	v_add_f32_e64 v91, v123, v91
	v_cvt_pk_bf16_f32 v95, v122, v123
	s_waitcnt lgkmcnt(1)
	v_mfma_f32_32x32x16_bf16 v[34:49], v[124:127], v[74:77], v[34:49]
	ds_read_b128 v[120:123], v0 offset:4704
	v_add_f32_e64 v90, v96, v90
	v_add_f32_e64 v91, v97, v91
	v_cvt_pk_bf16_f32 v96, v96, v97
	v_add_f32_e64 v90, v132, v90
	v_add_f32_e64 v91, v133, v91
	v_cvt_pk_bf16_f32 v97, v132, v133
	s_waitcnt lgkmcnt(1)
	v_mfma_f32_32x32x16_bf16 v[50:65], v[116:119], v[78:81], v[50:65]
	v_add_f32_e64 v116, v134, v90
	v_add_f32_e64 v117, v135, v91
	v_cvt_pk_bf16_f32 v90, v134, v135
	v_add_f32_e64 v116, v136, v116
	v_add_f32_e64 v117, v137, v117
	v_cvt_pk_bf16_f32 v91, v136, v137
	s_waitcnt lgkmcnt(0)
	v_mfma_f32_32x32x16_bf16 v[34:49], v[120:123], v[78:81], v[34:49]
	v_add_f32_e64 v116, v92, v116
	v_add_f32_e64 v117, v93, v117
	v_cvt_pk_bf16_f32 v92, v92, v93
	v_add_f32_e64 v116, v138, v116
	v_add_f32_e64 v117, v139, v117
	v_cvt_pk_bf16_f32 v93, v138, v139
	s_nop 0
	v_add_f32_e32 v0, v116, v117
	v_max_f32_e32 v116, v51, v51
	v_max_f32_e32 v117, v50, v50
	v_max_f32_e32 v116, v117, v116
	v_max3_f32 v116, v116, v52, v53
	v_max3_f32 v116, v116, v54, v55
	v_max3_f32 v116, v116, v56, v57
	v_max3_f32 v116, v116, v58, v59
	v_max3_f32 v116, v116, v60, v61
	v_max3_f32 v116, v116, v62, v63
	v_max3_f32 v116, v116, v64, v65
	v_max3_f32 v116, v116, v34, v35
	v_max3_f32 v116, v116, v36, v37
	v_max3_f32 v116, v116, v38, v39
	v_max3_f32 v116, v116, v40, v41
	v_max3_f32 v116, v116, v42, v43
	v_max3_f32 v116, v116, v44, v45
	v_max3_f32 v116, v116, v46, v47
	v_max3_f32 v116, v116, v48, v49
	v_add_f32_e32 v157, v157, v0
	ds_bpermute_b32 v0, v156, v116
	s_waitcnt lgkmcnt(0)
	v_max_f32_e32 v0, v0, v0
	v_max_f32_e32 v0, v116, v0
	v_cmp_lt_f32_e32 vcc, s33, v0
	s_cmp_lg_u64 vcc, 0
	s_cselect_b64 s[14:15], -1, 0
	s_cbranch_vccz .LBB0_397
	v_max_f32_e32 v0, v0, v0
	v_max_f32_e32 v116, 0, v0
	v_exp_f32_e64 v0, -v116
	v_add_f32_e32 v158, v158, v116
	v_xor_b32_e32 v220, 0x80000000, v158
	v_mov_b32_e32 v221, v220
	v_mov_b32_e32 v222, v220
	v_mov_b32_e32 v223, v220
	v_mov_b32_e32 v224, v220
	v_mov_b32_e32 v225, v220
	v_mov_b32_e32 v226, v220
	v_mov_b32_e32 v227, v220
	v_mov_b32_e32 v228, v220
	v_mov_b32_e32 v229, v220
	v_mov_b32_e32 v230, v220
	v_mov_b32_e32 v231, v220
	v_mov_b32_e32 v232, v220
	v_mov_b32_e32 v233, v220
	v_mov_b32_e32 v234, v220
	v_mov_b32_e32 v235, v220
	v_pk_add_f32 v[50:51], v[50:51], v[116:117] op_sel_hi:[1,0] neg_lo:[0,1] neg_hi:[0,1]
	v_pk_add_f32 v[34:35], v[34:35], v[116:117] op_sel_hi:[1,0] neg_lo:[0,1] neg_hi:[0,1]
	v_pk_add_f32 v[52:53], v[52:53], v[116:117] op_sel_hi:[1,0] neg_lo:[0,1] neg_hi:[0,1]
	v_pk_add_f32 v[36:37], v[36:37], v[116:117] op_sel_hi:[1,0] neg_lo:[0,1] neg_hi:[0,1]
	v_pk_add_f32 v[54:55], v[54:55], v[116:117] op_sel_hi:[1,0] neg_lo:[0,1] neg_hi:[0,1]
	v_pk_add_f32 v[38:39], v[38:39], v[116:117] op_sel_hi:[1,0] neg_lo:[0,1] neg_hi:[0,1]
	v_pk_add_f32 v[56:57], v[56:57], v[116:117] op_sel_hi:[1,0] neg_lo:[0,1] neg_hi:[0,1]
	v_pk_add_f32 v[40:41], v[40:41], v[116:117] op_sel_hi:[1,0] neg_lo:[0,1] neg_hi:[0,1]
	v_pk_add_f32 v[58:59], v[58:59], v[116:117] op_sel_hi:[1,0] neg_lo:[0,1] neg_hi:[0,1]
	v_pk_add_f32 v[42:43], v[42:43], v[116:117] op_sel_hi:[1,0] neg_lo:[0,1] neg_hi:[0,1]
	v_pk_add_f32 v[60:61], v[60:61], v[116:117] op_sel_hi:[1,0] neg_lo:[0,1] neg_hi:[0,1]
	v_pk_add_f32 v[44:45], v[44:45], v[116:117] op_sel_hi:[1,0] neg_lo:[0,1] neg_hi:[0,1]
	v_pk_add_f32 v[62:63], v[62:63], v[116:117] op_sel_hi:[1,0] neg_lo:[0,1] neg_hi:[0,1]
	v_pk_add_f32 v[46:47], v[46:47], v[116:117] op_sel_hi:[1,0] neg_lo:[0,1] neg_hi:[0,1]
	v_pk_add_f32 v[64:65], v[64:65], v[116:117] op_sel_hi:[1,0] neg_lo:[0,1] neg_hi:[0,1]
	v_pk_add_f32 v[48:49], v[48:49], v[116:117] op_sel_hi:[1,0] neg_lo:[0,1] neg_hi:[0,1]
	v_mul_f32_e32 v157, v157, v0
	s_branch .LBB0_398

.LBB0_418:
	s_mov_b32 s6, 0xf149f2ca
	s_waitcnt lgkmcnt(0)
	v_max3_f32 v158, v35, v38, s6
	v_sub_f32_e32 v2, v2, v158
	v_exp_f32_e32 v116, v2
	v_sub_f32_e32 v2, v18, v158
	v_exp_f32_e32 v124, v2
	v_sub_f32_e32 v2, v3, v158
	v_exp_f32_e32 v117, v2
	v_sub_f32_e32 v2, v19, v158
	v_exp_f32_e32 v125, v2
	v_sub_f32_e32 v2, v4, v158
	v_exp_f32_e32 v118, v2
	v_sub_f32_e32 v2, v20, v158
	v_exp_f32_e32 v128, v2
	v_sub_f32_e32 v2, v5, v158
	v_exp_f32_e32 v119, v2
	v_sub_f32_e32 v2, v21, v158
	v_exp_f32_e32 v129, v2
	v_sub_f32_e32 v2, v6, v158
	v_exp_f32_e32 v104, v2
	v_sub_f32_e32 v2, v22, v158
	v_exp_f32_e32 v96, v2
	v_sub_f32_e32 v2, v7, v158
	v_exp_f32_e32 v105, v2
	v_sub_f32_e32 v2, v23, v158
	v_exp_f32_e32 v97, v2
	v_sub_f32_e32 v2, v8, v158
	v_exp_f32_e32 v120, v2
	v_sub_f32_e32 v2, v24, v158
	v_exp_f32_e32 v132, v2
	v_sub_f32_e32 v2, v9, v158
	v_exp_f32_e32 v121, v2
	v_sub_f32_e32 v2, v25, v158
	v_exp_f32_e32 v133, v2
	v_sub_f32_e32 v2, v10, v158
	v_exp_f32_e32 v122, v2
	v_sub_f32_e32 v2, v26, v158
	v_exp_f32_e32 v134, v2
	v_sub_f32_e32 v2, v11, v158
	v_exp_f32_e32 v123, v2
	v_sub_f32_e32 v2, v27, v158
	v_exp_f32_e32 v135, v2
	v_sub_f32_e32 v2, v12, v158
	v_exp_f32_e32 v126, v2
	v_sub_f32_e32 v2, v28, v158
	v_exp_f32_e32 v136, v2
	v_sub_f32_e32 v2, v13, v158
	v_exp_f32_e32 v127, v2
	v_sub_f32_e32 v2, v29, v158
	v_exp_f32_e32 v137, v2
	v_sub_f32_e32 v2, v14, v158
	v_exp_f32_e32 v100, v2
	v_sub_f32_e32 v2, v30, v158
	v_exp_f32_e32 v92, v2
	v_sub_f32_e32 v2, v15, v158
	v_exp_f32_e32 v101, v2
	v_sub_f32_e32 v2, v31, v158
	v_exp_f32_e32 v93, v2
	v_sub_f32_e32 v2, v16, v158
	v_exp_f32_e32 v130, v2
	v_sub_f32_e32 v2, v32, v158
	v_exp_f32_e32 v138, v2
	v_sub_f32_e32 v2, v17, v158
	v_exp_f32_e32 v131, v2
	v_sub_f32_e32 v2, 0xf149f2ca, v158
	v_exp_f32_e32 v2, v2
	v_sub_f32_e32 v3, v33, v158
	v_exp_f32_e32 v139, v3
	v_and_b32_e32 v36, 31, v36
	v_mul_u32_u24_e32 v36, 0x50, v36
	v_mov_b32_e32 v33, 0
	v_mul_f32_e32 v111, 0, v2
	v_add_u32_e32 v154, v36, v0
	s_and_b64 vcc, exec, s[0:1]
	s_mov_b32 s19, 0
	s_barrier
	s_cbranch_vccnz .LBB0_377
	v_add_u32_e32 v159, s8, v149
	v_max_i32_e32 v0, 4, v159
	v_add_u32_e32 v0, -4, v0
	v_lshlrev_b32_e32 v161, 3, v153
	v_min_u32_e32 v160, 56, v0
	v_sub_u32_e32 v0, v161, v151
	v_or_b32_e32 v163, 1, v161
	v_cmp_gt_u32_e64 s[36:37], 16, v0
	v_sub_u32_e32 v0, v163, v151
	v_or_b32_e32 v164, 2, v161
	v_cmp_gt_u32_e64 s[38:39], 16, v0
	v_sub_u32_e32 v0, v164, v151
	v_or_b32_e32 v165, 3, v161
	v_cmp_gt_u32_e64 s[40:41], 16, v0
	v_sub_u32_e32 v0, v165, v151
	v_or_b32_e32 v166, 4, v161
	v_cmp_gt_u32_e64 s[42:43], 16, v0
	v_sub_u32_e32 v0, v166, v151
	v_or_b32_e32 v167, 5, v161
	v_cmp_gt_u32_e64 s[44:45], 16, v0
	v_sub_u32_e32 v0, v167, v151
	v_or_b32_e32 v168, 6, v161
	v_cmp_gt_u32_e64 s[46:47], 16, v0
	v_sub_u32_e32 v0, v168, v151
	v_or_b32_e32 v169, 7, v161
	s_lshl_b32 s16, s10, 6
	v_cmp_gt_u32_e64 s[10:11], 16, v0
	v_sub_u32_e32 v0, v169, v151
	v_or_b32_e32 v170, 16, v161
	v_cmp_gt_u32_e64 s[50:51], 16, v0
	v_sub_u32_e32 v0, v170, v151
	v_or_b32_e32 v171, 17, v161
	v_cmp_gt_u32_e64 s[52:53], 16, v0
	v_sub_u32_e32 v0, v171, v151
	v_or_b32_e32 v172, 18, v161
	v_cmp_gt_u32_e64 s[54:55], 16, v0
	v_sub_u32_e32 v0, v172, v151
	v_or_b32_e32 v173, 19, v161
	v_cmp_gt_u32_e64 s[56:57], 16, v0
	v_sub_u32_e32 v0, v173, v151
	v_or_b32_e32 v174, 20, v161
	v_cmp_gt_u32_e64 s[58:59], 16, v0
	v_sub_u32_e32 v0, v174, v151
	v_or_b32_e32 v175, 21, v161
	v_cmp_gt_u32_e64 s[60:61], 16, v0
	v_sub_u32_e32 v0, v175, v151
	v_or_b32_e32 v176, 22, v161
	v_cmp_gt_u32_e64 s[62:63], 16, v0
	v_sub_u32_e32 v0, v176, v151
	v_or_b32_e32 v177, 23, v161
	v_cmp_gt_u32_e64 s[64:65], 16, v0
	v_sub_u32_e32 v0, v177, v151
	v_or_b32_e32 v178, 32, v161
	v_cmp_gt_u32_e64 s[66:67], 16, v0
	v_sub_u32_e32 v0, v178, v151
	v_or_b32_e32 v179, 33, v161
	s_mov_b64 s[28:29], s[68:69]
	v_cmp_gt_u32_e64 s[68:69], 16, v0
	v_sub_u32_e32 v0, v179, v151
	v_or_b32_e32 v180, 34, v161
	s_mov_b64 s[30:31], s[70:71]
	v_cmp_gt_u32_e64 s[70:71], 16, v0
	v_sub_u32_e32 v0, v180, v151
	v_or_b32_e32 v181, 35, v161
	s_mov_b32 s24, s72
	v_cmp_gt_u32_e64 s[72:73], 16, v0
	v_sub_u32_e32 v0, v181, v151
	v_or_b32_e32 v182, 36, v161
	v_cmp_gt_u32_e64 s[74:75], 16, v0
	v_sub_u32_e32 v0, v182, v151
	v_or_b32_e32 v183, 37, v161
	v_cmp_gt_u32_e64 s[76:77], 16, v0
	v_sub_u32_e32 v0, v183, v151
	v_or_b32_e32 v184, 38, v161
	v_cmp_gt_u32_e64 s[78:79], 16, v0
	v_sub_u32_e32 v0, v184, v151
	v_or_b32_e32 v185, 39, v161
	v_mov_b32_e32 v35, v1
	v_cmp_gt_u32_e64 s[0:1], 16, v0
	v_sub_u32_e32 v0, v185, v151
	v_or_b32_e32 v186, 48, v161
	v_or_b32_e32 v187, 49, v161
	v_or_b32_e32 v188, 50, v161
	v_or_b32_e32 v189, 51, v161
	v_or_b32_e32 v190, 52, v161
	v_or_b32_e32 v191, 53, v161
	v_or_b32_e32 v192, 54, v161
	v_or_b32_e32 v193, 55, v161
	v_mov_b32_e32 v2, 0
	s_mov_b32 s6, 1
	v_lshl_add_u64 v[114:115], s[4:5], 0, v[34:35]
	s_add_i32 s8, s3, 16
	v_add_u32_e32 v162, 8, v160
	v_cmp_gt_u32_e64 s[82:83], 16, v0
	v_cmp_lt_u32_e64 s[84:85], v186, v152
	v_cmp_lt_u32_e64 s[86:87], v187, v152
	v_cmp_lt_u32_e64 s[88:89], v188, v152
	v_cmp_lt_u32_e64 s[90:91], v189, v152
	v_cmp_lt_u32_e64 s[92:93], v190, v152
	v_cmp_lt_u32_e64 s[94:95], v191, v152
	v_cmp_lt_u32_e64 s[96:97], v192, v152
	v_cmp_lt_u32_e64 s[4:5], v193, v152
	s_mov_b32 s17, 0
	s_mov_b32 s18, -15
	s_mov_b32 s21, 0
	v_mov_b32_e32 v3, v2
	v_mov_b32_e32 v4, v2
	v_mov_b32_e32 v5, v2
	v_mov_b32_e32 v6, v2
	v_mov_b32_e32 v7, v2
	v_mov_b32_e32 v8, v2
	v_mov_b32_e32 v9, v2
	v_mov_b32_e32 v10, v2
	v_mov_b32_e32 v11, v2
	v_mov_b32_e32 v12, v2
	v_mov_b32_e32 v13, v2
	v_mov_b32_e32 v14, v2
	v_mov_b32_e32 v15, v2
	v_mov_b32_e32 v16, v2
	v_mov_b32_e32 v17, v2
	v_mov_b32_e32 v18, v2
	v_mov_b32_e32 v19, v2
	v_mov_b32_e32 v20, v2
	v_mov_b32_e32 v21, v2
	v_mov_b32_e32 v22, v2
	v_mov_b32_e32 v23, v2
	v_mov_b32_e32 v24, v2
	v_mov_b32_e32 v25, v2
	v_mov_b32_e32 v26, v2
	v_mov_b32_e32 v27, v2
	v_mov_b32_e32 v28, v2
	v_mov_b32_e32 v29, v2
	v_mov_b32_e32 v30, v2
	v_mov_b32_e32 v31, v2
	v_mov_b32_e32 v32, v2
	v_mov_b32_e32 v33, v2
	v_xor_b32_e32 v220, 0x80000000, v158
	v_mov_b32_e32 v221, v220
	v_mov_b32_e32 v222, v220
	v_mov_b32_e32 v223, v220
	v_mov_b32_e32 v224, v220
	v_mov_b32_e32 v225, v220
	v_mov_b32_e32 v226, v220
	v_mov_b32_e32 v227, v220
	v_mov_b32_e32 v228, v220
	v_mov_b32_e32 v229, v220
	v_mov_b32_e32 v230, v220
	v_mov_b32_e32 v231, v220
	v_mov_b32_e32 v232, v220
	v_mov_b32_e32 v233, v220
	v_mov_b32_e32 v234, v220
	v_mov_b32_e32 v235, v220

.LBB0_422:
	s_mul_i32 s19, s20, 0x4c00
	v_add_u32_e32 v0, s19, v157
	ds_read_b128 v[206:209], v0
	ds_read_b128 v[210:213], v0 offset:4608
	ds_read_b128 v[214:217], v0 offset:32
	s_waitcnt lgkmcnt(2)
	v_mfma_f32_32x32x16_bf16 v[50:65], v[206:209], v[66:69], v[220:235]
	v_add_f32_e64 v90, v116, 0
	v_add_f32_e64 v91, v117, 0
	v_cvt_pk_bf16_f32 v102, v116, v117
	v_add_f32_e64 v90, v118, v90
	v_add_f32_e64 v91, v119, v91
	v_cvt_pk_bf16_f32 v103, v118, v119
	s_waitcnt lgkmcnt(1)
	v_mfma_f32_32x32x16_bf16 v[34:49], v[210:213], v[66:69], v[220:235]
	ds_read_b128 v[116:119], v0 offset:4640
	v_add_f32_e64 v90, v104, v90
	v_add_f32_e64 v91, v105, v91
	v_cvt_pk_bf16_f32 v104, v104, v105
	v_add_f32_e64 v90, v120, v90
	v_add_f32_e64 v91, v121, v91
	v_cvt_pk_bf16_f32 v105, v120, v121
	s_waitcnt lgkmcnt(1)
	v_mfma_f32_32x32x16_bf16 v[50:65], v[214:217], v[70:73], v[50:65]
	ds_read_b128 v[206:209], v0 offset:64
	v_add_f32_e64 v90, v122, v90
	v_add_f32_e64 v91, v123, v91
	v_cvt_pk_bf16_f32 v98, v122, v123
	v_add_f32_e64 v90, v126, v90
	v_add_f32_e64 v91, v127, v91
	v_cvt_pk_bf16_f32 v99, v126, v127
	s_waitcnt lgkmcnt(1)
	v_mfma_f32_32x32x16_bf16 v[34:49], v[116:119], v[70:73], v[34:49]
	ds_read_b128 v[120:123], v0 offset:4672
	v_add_f32_e64 v90, v100, v90
	v_add_f32_e64 v91, v101, v91
	v_cvt_pk_bf16_f32 v100, v100, v101
	v_add_f32_e64 v90, v130, v90
	v_add_f32_e64 v91, v131, v91
	v_cvt_pk_bf16_f32 v101, v130, v131
	s_waitcnt lgkmcnt(1)
	v_mfma_f32_32x32x16_bf16 v[50:65], v[206:209], v[74:77], v[50:65]
	ds_read_b128 v[116:119], v0 offset:96
	v_add_f32_e64 v90, v124, v90
	v_add_f32_e64 v91, v125, v91
	v_cvt_pk_bf16_f32 v94, v124, v125
	v_add_f32_e64 v90, v128, v90
	v_add_f32_e64 v91, v129, v91
	v_cvt_pk_bf16_f32 v95, v128, v129
	s_waitcnt lgkmcnt(1)
	v_mfma_f32_32x32x16_bf16 v[34:49], v[120:123], v[74:77], v[34:49]
	ds_read_b128 v[124:127], v0 offset:4704
	v_add_f32_e64 v90, v96, v90
	v_add_f32_e64 v91, v97, v91
	v_cvt_pk_bf16_f32 v96, v96, v97
	v_add_f32_e64 v90, v132, v90
	v_add_f32_e64 v91, v133, v91
	v_cvt_pk_bf16_f32 v97, v132, v133
	s_waitcnt lgkmcnt(1)
	v_mfma_f32_32x32x16_bf16 v[50:65], v[116:119], v[78:81], v[50:65]
	v_add_f32_e64 v116, v134, v90
	v_add_f32_e64 v117, v135, v91
	v_cvt_pk_bf16_f32 v90, v134, v135
	v_add_f32_e64 v116, v136, v116
	v_add_f32_e64 v117, v137, v117
	v_cvt_pk_bf16_f32 v91, v136, v137
	s_waitcnt lgkmcnt(0)
	v_mfma_f32_32x32x16_bf16 v[34:49], v[124:127], v[78:81], v[34:49]
	v_add_f32_e64 v116, v92, v116
	v_add_f32_e64 v117, v93, v117
	v_cvt_pk_bf16_f32 v92, v92, v93
	v_add_f32_e64 v116, v138, v116
	v_add_f32_e64 v117, v139, v117
	v_cvt_pk_bf16_f32 v93, v138, v139
	s_cmp_lt_u32 s7, 8
	s_cbranch_scc1 .LBB0_424
	s_add_i32 s6, s16, s17
	s_addk_i32 s6, 0xfe40
	s_ashr_i32 s22, s6, 6
	v_sub_u32_e32 v0, s22, v159
	v_mul_lo_u32 v0, v0, 31
	v_sub_u32_e32 v0, v0, v150
	v_add_u32_e32 v0, 0xe8, v0
	v_add_u32_e32 v118, v0, v161
	v_med3_i32 v118, v118, 0, v204
	v_lshl_add_u32 v118, v118, 2, v203
	ds_read_b32 v118, v118
	v_cmp_ge_i32_e64 s[6:7], s22, v160
	v_cmp_lt_i32_e32 vcc, s22, v162
	s_and_b64 s[6:7], s[6:7], vcc
	s_and_b64 vcc, s[6:7], s[36:37]
	s_waitcnt lgkmcnt(0)
	v_add_f32_e32 v50, v50, v118
	v_add_u32_e32 v118, v0, v163
	v_med3_i32 v118, v118, 0, v204
	v_lshl_add_u32 v118, v118, 2, v203
	ds_read_b32 v118, v118
	v_cndmask_b32_e32 v50, v201, v50, vcc
	s_and_b64 vcc, s[6:7], s[38:39]
	s_waitcnt lgkmcnt(0)
	v_add_f32_e32 v51, v51, v118
	v_add_u32_e32 v118, v0, v164
	v_med3_i32 v118, v118, 0, v204
	v_lshl_add_u32 v118, v118, 2, v203
	ds_read_b32 v118, v118
	v_cndmask_b32_e32 v51, v201, v51, vcc
	s_and_b64 vcc, s[6:7], s[40:41]
	s_waitcnt lgkmcnt(0)
	v_add_f32_e32 v52, v52, v118
	v_add_u32_e32 v118, v0, v165
	v_med3_i32 v118, v118, 0, v204
	v_lshl_add_u32 v118, v118, 2, v203
	ds_read_b32 v118, v118
	v_cndmask_b32_e32 v52, v201, v52, vcc
	s_and_b64 vcc, s[6:7], s[42:43]
	s_waitcnt lgkmcnt(0)
	v_add_f32_e32 v53, v53, v118
	v_add_u32_e32 v118, v0, v166
	v_med3_i32 v118, v118, 0, v204
	v_lshl_add_u32 v118, v118, 2, v203
	ds_read_b32 v118, v118
	v_cndmask_b32_e32 v53, v201, v53, vcc
	s_and_b64 vcc, s[6:7], s[44:45]
	s_waitcnt lgkmcnt(0)
	v_add_f32_e32 v54, v54, v118
	v_add_u32_e32 v118, v0, v167
	v_med3_i32 v118, v118, 0, v204
	v_lshl_add_u32 v118, v118, 2, v203
	ds_read_b32 v118, v118
	v_cndmask_b32_e32 v54, v201, v54, vcc
	s_and_b64 vcc, s[6:7], s[46:47]
	s_waitcnt lgkmcnt(0)
	v_add_f32_e32 v55, v55, v118
	v_add_u32_e32 v118, v0, v168
	v_med3_i32 v118, v118, 0, v204
	v_lshl_add_u32 v118, v118, 2, v203
	ds_read_b32 v118, v118
	v_cndmask_b32_e32 v55, v201, v55, vcc
	s_and_b64 vcc, s[6:7], s[10:11]
	s_waitcnt lgkmcnt(0)
	v_add_f32_e32 v56, v56, v118
	v_add_u32_e32 v118, v0, v169
	v_med3_i32 v118, v118, 0, v204
	v_lshl_add_u32 v118, v118, 2, v203
	ds_read_b32 v118, v118
	v_cndmask_b32_e32 v56, v201, v56, vcc
	s_and_b64 vcc, s[6:7], s[50:51]
	s_waitcnt lgkmcnt(0)
	v_add_f32_e32 v57, v57, v118
	v_add_u32_e32 v118, v0, v170
	v_med3_i32 v118, v118, 0, v204
	v_lshl_add_u32 v118, v118, 2, v203
	ds_read_b32 v118, v118
	v_cndmask_b32_e32 v57, v201, v57, vcc
	s_and_b64 vcc, s[6:7], s[52:53]
	s_waitcnt lgkmcnt(0)
	v_add_f32_e32 v58, v58, v118
	v_add_u32_e32 v118, v0, v171
	v_med3_i32 v118, v118, 0, v204
	v_lshl_add_u32 v118, v118, 2, v203
	ds_read_b32 v118, v118
	v_cndmask_b32_e32 v58, v201, v58, vcc
	s_and_b64 vcc, s[6:7], s[54:55]
	s_waitcnt lgkmcnt(0)
	v_add_f32_e32 v59, v59, v118
	v_add_u32_e32 v118, v0, v172
	v_med3_i32 v118, v118, 0, v204
	v_lshl_add_u32 v118, v118, 2, v203
	ds_read_b32 v118, v118
	v_cndmask_b32_e32 v59, v201, v59, vcc
	s_and_b64 vcc, s[6:7], s[56:57]
	s_waitcnt lgkmcnt(0)
	v_add_f32_e32 v60, v60, v118
	v_add_u32_e32 v118, v0, v173
	v_med3_i32 v118, v118, 0, v204
	v_lshl_add_u32 v118, v118, 2, v203
	ds_read_b32 v118, v118
	v_cndmask_b32_e32 v60, v201, v60, vcc
	s_and_b64 vcc, s[6:7], s[58:59]
	s_waitcnt lgkmcnt(0)
	v_add_f32_e32 v61, v61, v118
	v_add_u32_e32 v118, v0, v174
	v_med3_i32 v118, v118, 0, v204
	v_lshl_add_u32 v118, v118, 2, v203
	ds_read_b32 v118, v118
	v_cndmask_b32_e32 v61, v201, v61, vcc
	s_and_b64 vcc, s[6:7], s[60:61]
	s_waitcnt lgkmcnt(0)
	v_add_f32_e32 v62, v62, v118
	v_add_u32_e32 v118, v0, v175
	v_med3_i32 v118, v118, 0, v204
	v_lshl_add_u32 v118, v118, 2, v203
	ds_read_b32 v118, v118
	v_cndmask_b32_e32 v62, v201, v62, vcc
	s_and_b64 vcc, s[6:7], s[62:63]
	s_waitcnt lgkmcnt(0)
	v_add_f32_e32 v63, v63, v118
	v_add_u32_e32 v118, v0, v176
	v_med3_i32 v118, v118, 0, v204
	v_lshl_add_u32 v118, v118, 2, v203
	ds_read_b32 v118, v118
	v_cndmask_b32_e32 v63, v201, v63, vcc
	s_and_b64 vcc, s[6:7], s[64:65]
	s_waitcnt lgkmcnt(0)
	v_add_f32_e32 v64, v64, v118
	v_add_u32_e32 v118, v0, v177
	v_med3_i32 v118, v118, 0, v204
	v_lshl_add_u32 v118, v118, 2, v203
	ds_read_b32 v118, v118
	v_cndmask_b32_e32 v64, v201, v64, vcc
	s_and_b64 vcc, s[6:7], s[66:67]
	s_waitcnt lgkmcnt(0)
	v_add_f32_e32 v65, v65, v118
	v_add_u32_e32 v118, v0, v178
	v_med3_i32 v118, v118, 0, v204
	v_lshl_add_u32 v118, v118, 2, v203
	ds_read_b32 v118, v118
	v_cndmask_b32_e32 v65, v201, v65, vcc
	s_and_b64 vcc, s[6:7], s[68:69]
	s_waitcnt lgkmcnt(0)
	v_add_f32_e32 v34, v34, v118
	v_add_u32_e32 v118, v0, v179
	v_med3_i32 v118, v118, 0, v204
	v_lshl_add_u32 v118, v118, 2, v203
	ds_read_b32 v118, v118
	v_cndmask_b32_e32 v34, v201, v34, vcc
	s_and_b64 vcc, s[6:7], s[70:71]
	s_waitcnt lgkmcnt(0)
	v_add_f32_e32 v35, v35, v118
	v_add_u32_e32 v118, v0, v180
	v_med3_i32 v118, v118, 0, v204
	v_lshl_add_u32 v118, v118, 2, v203
	ds_read_b32 v118, v118
	v_cndmask_b32_e32 v35, v201, v35, vcc
	s_and_b64 vcc, s[6:7], s[72:73]
	s_waitcnt lgkmcnt(0)
	v_add_f32_e32 v36, v36, v118
	v_add_u32_e32 v118, v0, v181
	v_med3_i32 v118, v118, 0, v204
	v_lshl_add_u32 v118, v118, 2, v203
	ds_read_b32 v118, v118
	v_cndmask_b32_e32 v36, v201, v36, vcc
	s_and_b64 vcc, s[6:7], s[74:75]
	s_waitcnt lgkmcnt(0)
	v_add_f32_e32 v37, v37, v118
	v_add_u32_e32 v118, v0, v182
	v_med3_i32 v118, v118, 0, v204
	v_lshl_add_u32 v118, v118, 2, v203
	ds_read_b32 v118, v118
	v_cndmask_b32_e32 v37, v201, v37, vcc
	s_and_b64 vcc, s[6:7], s[76:77]
	s_waitcnt lgkmcnt(0)
	v_add_f32_e32 v38, v38, v118
	v_add_u32_e32 v118, v0, v183
	v_med3_i32 v118, v118, 0, v204
	v_lshl_add_u32 v118, v118, 2, v203
	ds_read_b32 v118, v118
	v_cndmask_b32_e32 v38, v201, v38, vcc
	s_and_b64 vcc, s[6:7], s[78:79]
	s_waitcnt lgkmcnt(0)
	v_add_f32_e32 v39, v39, v118
	v_add_u32_e32 v118, v0, v184
	v_med3_i32 v118, v118, 0, v204
	v_lshl_add_u32 v118, v118, 2, v203
	ds_read_b32 v118, v118
	v_cndmask_b32_e32 v39, v201, v39, vcc
	s_and_b64 vcc, s[6:7], s[0:1]
	s_waitcnt lgkmcnt(0)
	v_add_f32_e32 v40, v40, v118
	v_add_u32_e32 v118, v0, v185
	v_med3_i32 v118, v118, 0, v204
	v_lshl_add_u32 v118, v118, 2, v203
	ds_read_b32 v118, v118
	v_cndmask_b32_e32 v40, v201, v40, vcc
	s_and_b64 vcc, s[6:7], s[82:83]
	s_waitcnt lgkmcnt(0)
	v_add_f32_e32 v41, v41, v118
	v_add_u32_e32 v118, v0, v186
	v_med3_i32 v118, v118, 0, v204
	v_lshl_add_u32 v118, v118, 2, v203
	ds_read_b32 v118, v118
	v_cndmask_b32_e32 v41, v201, v41, vcc
	s_and_b64 vcc, s[6:7], s[84:85]
	s_waitcnt lgkmcnt(0)
	v_add_f32_e32 v42, v42, v118
	v_add_u32_e32 v118, v0, v187
	v_med3_i32 v118, v118, 0, v204
	v_lshl_add_u32 v118, v118, 2, v203
	ds_read_b32 v118, v118
	v_cndmask_b32_e32 v42, v201, v42, vcc
	s_and_b64 vcc, s[6:7], s[86:87]
	s_waitcnt lgkmcnt(0)
	v_add_f32_e32 v43, v43, v118
	v_add_u32_e32 v118, v0, v188
	v_med3_i32 v118, v118, 0, v204
	v_lshl_add_u32 v118, v118, 2, v203
	ds_read_b32 v118, v118
	v_cndmask_b32_e32 v43, v201, v43, vcc
	s_and_b64 vcc, s[6:7], s[88:89]
	s_waitcnt lgkmcnt(0)
	v_add_f32_e32 v44, v44, v118
	v_add_u32_e32 v118, v0, v189
	v_med3_i32 v118, v118, 0, v204
	v_lshl_add_u32 v118, v118, 2, v203
	ds_read_b32 v118, v118
	v_cndmask_b32_e32 v44, v201, v44, vcc
	s_and_b64 vcc, s[6:7], s[90:91]
	s_waitcnt lgkmcnt(0)
	v_add_f32_e32 v45, v45, v118
	v_add_u32_e32 v118, v0, v190
	v_med3_i32 v118, v118, 0, v204
	v_lshl_add_u32 v118, v118, 2, v203
	ds_read_b32 v118, v118
	v_cndmask_b32_e32 v45, v201, v45, vcc
	s_and_b64 vcc, s[6:7], s[92:93]
	s_waitcnt lgkmcnt(0)
	v_add_f32_e32 v46, v46, v118
	v_add_u32_e32 v118, v0, v191
	v_med3_i32 v118, v118, 0, v204
	v_lshl_add_u32 v118, v118, 2, v203
	ds_read_b32 v118, v118
	v_cndmask_b32_e32 v46, v201, v46, vcc
	s_and_b64 vcc, s[6:7], s[94:95]
	s_waitcnt lgkmcnt(0)
	v_add_f32_e32 v47, v47, v118
	v_add_u32_e32 v118, v0, v192
	v_med3_i32 v118, v118, 0, v204
	v_add_u32_e32 v0, v0, v193
	v_lshl_add_u32 v118, v118, 2, v203
	v_med3_i32 v0, v0, 0, v204
	ds_read_b32 v118, v118
	v_lshl_add_u32 v0, v0, 2, v203
	ds_read_b32 v0, v0
	v_cndmask_b32_e32 v47, v201, v47, vcc
	s_and_b64 vcc, s[6:7], s[96:97]
	s_waitcnt lgkmcnt(1)
	v_add_f32_e32 v48, v48, v118
	v_cndmask_b32_e32 v48, v201, v48, vcc
	s_and_b64 vcc, s[6:7], s[4:5]
	s_waitcnt lgkmcnt(0)
	v_add_f32_e32 v0, v49, v0
	v_cndmask_b32_e32 v49, v201, v0, vcc
.LBB0_424:
	v_add_f32_e32 v0, v116, v117
	v_add_f32_e32 v111, v111, v0
	v_max_f32_e32 v0, v51, v51
	v_max_f32_e32 v116, v50, v50
	v_max_f32_e32 v0, v116, v0
	v_max3_f32 v0, v0, v52, v53
	v_max3_f32 v0, v0, v54, v55
	v_max3_f32 v0, v0, v56, v57
	v_max3_f32 v0, v0, v58, v59
	v_max3_f32 v0, v0, v60, v61
	v_max3_f32 v0, v0, v62, v63
	v_max3_f32 v0, v0, v64, v65
	v_max3_f32 v0, v0, v34, v35
	v_max3_f32 v0, v0, v36, v37
	v_max3_f32 v0, v0, v38, v39
	v_max3_f32 v0, v0, v40, v41
	v_max3_f32 v0, v0, v42, v43
	v_max3_f32 v0, v0, v44, v45
	v_max3_f32 v0, v0, v46, v47
	v_max3_f32 v0, v0, v48, v49
	ds_bpermute_b32 v116, v109, v0
	s_waitcnt lgkmcnt(0)
	v_max_f32_e32 v116, v116, v116
	v_max_f32_e32 v0, v0, v116
	v_cmp_lt_f32_e32 vcc, s25, v0
	s_cmp_lg_u64 vcc, 0
	s_cselect_b64 s[6:7], -1, 0
	s_cbranch_vccz .LBB0_426
	v_max_f32_e32 v0, v0, v0
	v_max_f32_e32 v116, 0, v0
	v_exp_f32_e64 v0, -v116
	v_add_f32_e32 v158, v158, v116
	v_xor_b32_e32 v220, 0x80000000, v158
	v_mov_b32_e32 v221, v220
	v_mov_b32_e32 v222, v220
	v_mov_b32_e32 v223, v220
	v_mov_b32_e32 v224, v220
	v_mov_b32_e32 v225, v220
	v_mov_b32_e32 v226, v220
	v_mov_b32_e32 v227, v220
	v_mov_b32_e32 v228, v220
	v_mov_b32_e32 v229, v220
	v_mov_b32_e32 v230, v220
	v_mov_b32_e32 v231, v220
	v_mov_b32_e32 v232, v220
	v_mov_b32_e32 v233, v220
	v_mov_b32_e32 v234, v220
	v_mov_b32_e32 v235, v220
	v_pk_add_f32 v[50:51], v[50:51], v[116:117] op_sel_hi:[1,0] neg_lo:[0,1] neg_hi:[0,1]
	v_pk_add_f32 v[34:35], v[34:35], v[116:117] op_sel_hi:[1,0] neg_lo:[0,1] neg_hi:[0,1]
	v_pk_add_f32 v[52:53], v[52:53], v[116:117] op_sel_hi:[1,0] neg_lo:[0,1] neg_hi:[0,1]
	v_pk_add_f32 v[36:37], v[36:37], v[116:117] op_sel_hi:[1,0] neg_lo:[0,1] neg_hi:[0,1]
	v_pk_add_f32 v[54:55], v[54:55], v[116:117] op_sel_hi:[1,0] neg_lo:[0,1] neg_hi:[0,1]
	v_pk_add_f32 v[38:39], v[38:39], v[116:117] op_sel_hi:[1,0] neg_lo:[0,1] neg_hi:[0,1]
	v_pk_add_f32 v[56:57], v[56:57], v[116:117] op_sel_hi:[1,0] neg_lo:[0,1] neg_hi:[0,1]
	v_pk_add_f32 v[40:41], v[40:41], v[116:117] op_sel_hi:[1,0] neg_lo:[0,1] neg_hi:[0,1]
	v_pk_add_f32 v[58:59], v[58:59], v[116:117] op_sel_hi:[1,0] neg_lo:[0,1] neg_hi:[0,1]
	v_pk_add_f32 v[42:43], v[42:43], v[116:117] op_sel_hi:[1,0] neg_lo:[0,1] neg_hi:[0,1]
	v_pk_add_f32 v[60:61], v[60:61], v[116:117] op_sel_hi:[1,0] neg_lo:[0,1] neg_hi:[0,1]
	v_pk_add_f32 v[44:45], v[44:45], v[116:117] op_sel_hi:[1,0] neg_lo:[0,1] neg_hi:[0,1]
	v_pk_add_f32 v[62:63], v[62:63], v[116:117] op_sel_hi:[1,0] neg_lo:[0,1] neg_hi:[0,1]
	v_pk_add_f32 v[46:47], v[46:47], v[116:117] op_sel_hi:[1,0] neg_lo:[0,1] neg_hi:[0,1]
	v_pk_add_f32 v[64:65], v[64:65], v[116:117] op_sel_hi:[1,0] neg_lo:[0,1] neg_hi:[0,1]
	v_pk_add_f32 v[48:49], v[48:49], v[116:117] op_sel_hi:[1,0] neg_lo:[0,1] neg_hi:[0,1]
	v_mul_f32_e32 v111, v111, v0
	s_branch .LBB0_427

.LBB0_442:
	s_lshl_b32 s8, s7, 8
	s_ashr_i32 s5, s7, 4
	s_and_b32 s8, s8, 0xf00
	s_addk_i32 s7, 0xfc00
	s_and_b64 s[10:11], s[0:1], exec
	s_cselect_b32 s5, s5, s7
	s_cselect_b32 s7, s8, 0
	s_ashr_i32 s8, s5, 31
	s_lshr_b32 s8, s8, 29
	s_add_i32 s8, s5, s8
	s_ashr_i32 s12, s8, 3
	s_and_b32 s8, s8, 0x1fffff8
	s_lshl_b32 s10, s12, 12
	s_sub_i32 s8, s5, s8
	s_add_i32 s13, s10, 0x2000
	s_lshl_b32 s14, s12, 8
	s_and_b64 s[10:11], s[0:1], exec
	s_cselect_b32 s10, s13, s14
	s_add_i32 s10, s10, s7
	s_lshl_b32 s7, s12, 9
	s_add_i32 s13, s13, s7
	s_and_b64 s[0:1], s[0:1], exec
	v_add_u32_e32 v30, s10, v193
	s_cselect_b32 s10, s13, s14
	s_lshl_b32 s28, s4, 1
	v_readlane_b32 s0, v243, 9
	v_readlane_b32 s1, v243, 10
	s_add_u32 s4, s0, s28
	s_mul_i32 s0, s5, s6
	s_addc_u32 s7, s1, 0
	s_ashr_i32 s1, s0, 31
	s_lshl_b64 s[36:37], s[0:1], 13
	s_add_u32 s38, s4, s36
	s_addc_u32 s39, s7, s37
	v_ashrrev_i32_e32 v31, 31, v30
	s_lshl_b32 s0, s8, 7
	v_lshlrev_b64 v[2:3], 11, v[30:31]
	s_ashr_i32 s1, s0, 31
	v_mov_b32_e32 v54, v147
	v_lshl_add_u64 v[2:3], s[94:95], 0, v[2:3]
	s_lshl_b64 s[4:5], s[0:1], 1
	v_lshl_add_u64 v[152:153], v[2:3], 0, s[4:5]
	v_lshrrev_b32_e32 v16, 1, v54
	v_and_b32_e32 v0, 16, v16
	v_lshl_add_u64 v[2:3], v[152:153], 0, v[0:1]
	global_load_dwordx4 v[98:101], v[2:3], off
	global_load_dwordx4 v[102:105], v[2:3], off offset:32
	global_load_dwordx4 v[106:109], v[2:3], off offset:64
	global_load_dwordx4 v[110:113], v[2:3], off offset:96
	v_ashrrev_i32_e32 v2, 31, v54
	v_lshrrev_b32_e32 v2, 23, v2
	v_add_u32_e32 v2, v54, v2
	s_ashr_i32 s11, s10, 31
	v_ashrrev_i32_e32 v18, 9, v2
	v_and_b32_e32 v2, 0xfffffe00, v2
	s_lshl_b64 s[6:7], s[10:11], 11
	v_sub_u32_e32 v2, v54, v2
	s_add_u32 s8, s50, s6
	v_lshlrev_b32_e32 v3, 12, v18
	v_ashrrev_i32_e32 v19, 2, v2
	s_addc_u32 s10, s51, s7
	v_and_b32_e32 v17, 3, v54
	v_ashrrev_i32_e32 v14, 3, v54
	v_lshl_add_u32 v2, v19, 5, v3
	s_add_u32 s40, s8, s4
	v_lshl_or_b32 v2, v17, 3, v2
	v_ashrrev_i32_e32 v15, 31, v14
	v_lshlrev_b32_e32 v3, 4, v54
	s_addc_u32 s41, s10, s5
	v_lshlrev_b64 v[50:51], 11, v[14:15]
	v_and_b32_e32 v150, 0x70, v3
	v_ashrrev_i32_e32 v3, 31, v2
	v_lshl_add_u64 v[4:5], s[40:41], 0, v[50:51]
	v_mov_b32_e32 v151, v1
	v_lshlrev_b64 v[52:53], 1, v[2:3]
	v_lshl_add_u64 v[32:33], v[4:5], 0, v[150:151]
	v_lshl_add_u64 v[10:11], s[38:39], 0, v[52:53]
	s_movk_i32 s14, 0x2000
	s_barrier
	global_load_dwordx4 v[2:5], v[32:33], off
	global_load_dwordx4 v[6:9], v[10:11], off
	v_add_co_u32_e32 v10, vcc, s14, v10
	v_lshlrev_b32_e32 v15, 1, v54
	s_nop 0
	v_addc_co_u32_e32 v11, vcc, 0, v11, vcc
	global_load_dwordx4 v[10:13], v[10:11], off
	v_and_b32_e32 v20, 19, v54
	v_and_b32_e32 v15, 8, v15
	v_and_b32_e32 v16, 4, v16
	v_mul_lo_u32 v207, v14, s76
	v_or3_b32 v14, v20, v15, v16
	v_mad_u32_u24 v208, v14, s76, v0
	v_lshl_add_u32 v14, v18, 7, v19
	s_movk_i32 s29, 0x50
	v_add_u32_e32 v56, v207, v150
	v_mul_lo_u32 v14, v14, s29
	v_lshl_add_u32 v209, v17, 4, v14
	s_add_u32 s42, s38, 0x4000
	s_mov_b32 s15, 0x20000
	v_lshlrev_b64 v[148:149], 10, v[30:31]
	s_addc_u32 s43, s39, 0
	v_add_co_u32_e32 v30, vcc, s15, v32
	v_and_b32_e32 v151, 63, v54
	s_nop 0
	v_addc_co_u32_e32 v31, vcc, 0, v33, vcc
	v_lshl_add_u64 v[32:33], s[42:43], 0, v[52:53]
	v_and_b32_e32 v57, 31, v54
	v_add_co_u32_e32 v54, vcc, s14, v32
	s_mov_b32 s22, s9
	s_nop 0
	v_addc_co_u32_e32 v55, vcc, 0, v33, vcc
	s_mov_b32 s23, s9
	s_mov_b32 s8, s9
	s_mov_b32 s10, s9
	s_waitcnt vmcnt(2)
	ds_write_b128 v56, v[2:5]
	s_waitcnt vmcnt(1)
	ds_write_b128 v209, v[6:9] offset:9216
	s_waitcnt vmcnt(0)
	ds_write_b128 v209, v[10:13] offset:19456
	s_waitcnt lgkmcnt(0)
	s_barrier
	ds_read_b128 v[2:5], v208
	ds_read_b128 v[18:21], v208 offset:32
	s_waitcnt lgkmcnt(1)
	v_mfma_f32_32x32x16_bf16 v[2:17], v[2:5], v[98:101], 0
	ds_read_b128 v[22:25], v208 offset:4608
	ds_read_b128 v[26:29], v208 offset:4640
	s_mov_b32 s11, s9
	s_mov_b32 s12, s9
	s_mov_b32 s13, s9
	s_mov_b32 s14, s9
	s_mov_b32 s15, s9
	s_mov_b32 s16, s9
	s_waitcnt lgkmcnt(1)
	v_mfma_f32_32x32x16_bf16 v[34:49], v[22:25], v[98:101], 0
	ds_read_b128 v[22:25], v208 offset:64
	s_mov_b32 s17, s9
	s_mov_b32 s18, s9
	s_mov_b32 s19, s9
	s_mov_b32 s20, s9
	s_mov_b32 s21, s9
	s_add_u32 s36, s36, s28
	v_mfma_f32_32x32x16_bf16 v[2:17], v[18:21], v[102:105], v[2:17]
	ds_read_b128 v[18:21], v208 offset:96
	s_addc_u32 s37, s37, 0
	v_mad_u32_u24 v211, v57, s29, v0
	v_lshl_add_u64 v[156:157], s[36:37], 0, v[52:53]
	s_mov_b32 s30, 0x41000000
	s_mov_b64 s[52:53], 0x20000
	s_mov_b64 s[54:55], 0x4000
	s_waitcnt lgkmcnt(1)
	v_mfma_f32_32x32x16_bf16 v[2:17], v[22:25], v[106:109], v[2:17]
	ds_read_b128 v[22:25], v208 offset:4672
	global_load_dwordx4 v[114:117], v[30:31], off
	global_load_dwordx4 v[118:121], v[32:33], off
	global_load_dwordx4 v[122:125], v[54:55], off
	s_mov_b32 s25, 0
	s_mov_b32 s24, 1
	v_mfma_f32_32x32x16_bf16 v[34:49], v[26:29], v[102:105], v[34:49]
	s_waitcnt lgkmcnt(1)
	v_mfma_f32_32x32x16_bf16 v[2:17], v[18:21], v[110:113], v[2:17]
	ds_read_b128 v[18:21], v208 offset:4704
	s_waitcnt vmcnt(2)
	ds_write_b128 v56, v[114:117] offset:29696
	s_waitcnt vmcnt(1)
	ds_write_b128 v209, v[118:121] offset:38912
	s_waitcnt vmcnt(0)
	ds_write_b128 v209, v[122:125] offset:49152
	s_waitcnt lgkmcnt(4)
	v_mfma_f32_32x32x16_bf16 v[34:49], v[22:25], v[106:109], v[34:49]
	s_nop 2
	v_max_f32_e32 v26, v3, v3
	v_max_f32_e32 v27, v2, v2
	v_max_f32_e32 v26, v27, v26
	v_max3_f32 v22, v26, v4, v5
	v_max3_f32 v22, v22, v6, v7
	v_max3_f32 v22, v22, v8, v9
	v_max3_f32 v22, v22, v10, v11
	s_waitcnt lgkmcnt(3)
	v_mfma_f32_32x32x16_bf16 v[34:49], v[18:21], v[110:113], v[34:49]
	v_max3_f32 v22, v22, v12, v13
	v_max3_f32 v22, v22, v14, v15
	v_max3_f32 v22, v22, v16, v17
	s_waitcnt lgkmcnt(0)
	s_barrier
	s_nop 6
	v_max3_f32 v18, v22, v34, v35
	v_max3_f32 v18, v18, v36, v37
	v_max3_f32 v18, v18, v38, v39
	v_max3_f32 v18, v18, v40, v41
	v_max3_f32 v18, v18, v42, v43
	v_max3_f32 v18, v18, v44, v45
	v_max3_f32 v18, v18, v46, v47
	v_max3_f32 v54, v18, v48, v49
	ds_bpermute_b32 v55, v190, v54
	v_mov_b64_e32 v[32:33], s[22:23]
	v_mov_b64_e32 v[30:31], s[20:21]
	v_mov_b64_e32 v[28:29], s[18:19]
	v_mov_b64_e32 v[26:27], s[16:17]
	v_mov_b64_e32 v[24:25], s[14:15]
	v_mov_b64_e32 v[22:23], s[12:13]
	v_mov_b64_e32 v[20:21], s[10:11]
	v_mov_b64_e32 v[18:19], s[8:9]
	s_mov_b32 s8, 0xf149f2ca
	s_waitcnt lgkmcnt(0)
	v_max3_f32 v210, v54, v55, s8
	v_sub_f32_e32 v2, v2, v210
	v_exp_f32_e32 v158, v2
	v_sub_f32_e32 v2, v34, v210
	v_exp_f32_e32 v168, v2
	v_sub_f32_e32 v2, v3, v210
	v_exp_f32_e32 v159, v2
	v_sub_f32_e32 v2, v35, v210
	v_exp_f32_e32 v169, v2
	v_sub_f32_e32 v2, v4, v210
	v_exp_f32_e32 v160, v2
	v_sub_f32_e32 v2, v36, v210
	v_exp_f32_e32 v172, v2
	v_sub_f32_e32 v2, v5, v210
	v_exp_f32_e32 v161, v2
	v_sub_f32_e32 v2, v37, v210
	v_exp_f32_e32 v173, v2
	v_sub_f32_e32 v2, v6, v210
	v_exp_f32_e32 v162, v2
	v_sub_f32_e32 v2, v38, v210
	v_exp_f32_e32 v176, v2
	v_sub_f32_e32 v2, v7, v210
	v_exp_f32_e32 v163, v2
	v_sub_f32_e32 v2, v39, v210
	v_exp_f32_e32 v177, v2
	v_sub_f32_e32 v2, v8, v210
	v_exp_f32_e32 v164, v2
	v_sub_f32_e32 v2, v40, v210
	v_exp_f32_e32 v180, v2
	v_sub_f32_e32 v2, v9, v210
	v_exp_f32_e32 v165, v2
	v_sub_f32_e32 v2, v41, v210
	v_exp_f32_e32 v181, v2
	v_sub_f32_e32 v2, v10, v210
	v_exp_f32_e32 v166, v2
	v_sub_f32_e32 v2, v42, v210
	v_exp_f32_e32 v182, v2
	v_sub_f32_e32 v2, v11, v210
	v_exp_f32_e32 v167, v2
	v_sub_f32_e32 v2, v43, v210
	v_exp_f32_e32 v183, v2
	v_sub_f32_e32 v2, v12, v210
	v_exp_f32_e32 v170, v2
	v_sub_f32_e32 v2, v44, v210
	v_exp_f32_e32 v184, v2
	v_sub_f32_e32 v2, v13, v210
	v_exp_f32_e32 v171, v2
	v_sub_f32_e32 v2, v45, v210
	v_exp_f32_e32 v185, v2
	v_sub_f32_e32 v2, v14, v210
	v_exp_f32_e32 v174, v2
	v_sub_f32_e32 v2, v46, v210
	v_exp_f32_e32 v186, v2
	v_sub_f32_e32 v2, v15, v210
	v_exp_f32_e32 v175, v2
	v_sub_f32_e32 v2, v47, v210
	v_exp_f32_e32 v187, v2
	v_sub_f32_e32 v2, v16, v210
	v_exp_f32_e32 v178, v2
	v_sub_f32_e32 v2, v48, v210
	v_sub_f32_e32 v54, 0xf149f2ca, v210
	v_exp_f32_e32 v188, v2
	v_sub_f32_e32 v2, v17, v210
	v_exp_f32_e32 v54, v54
	v_exp_f32_e32 v179, v2
	v_sub_f32_e32 v2, v49, v210
	v_exp_f32_e32 v189, v2
	v_lshl_add_u64 v[2:3], v[50:51], 0, s[6:7]
	v_or_b32_e32 v2, v2, v150
	v_lshl_add_u64 v[2:3], v[2:3], 0, s[4:5]
	s_mov_b64 s[10:11], 0x7840000
	v_mul_f32_e32 v206, 0, v54
	v_lshl_add_u64 v[154:155], v[2:3], 0, s[10:11]
	v_mov_b64_e32 v[64:65], v[32:33]
	v_mov_b64_e32 v[48:49], v[32:33]
	v_mov_b64_e32 v[2:3], v[18:19]
	v_mov_b64_e32 v[62:63], v[30:31]
	v_mov_b64_e32 v[60:61], v[28:29]
	v_mov_b64_e32 v[58:59], v[26:27]
	v_mov_b64_e32 v[56:57], v[24:25]
	v_mov_b64_e32 v[54:55], v[22:23]
	v_mov_b64_e32 v[52:53], v[20:21]
	v_mov_b64_e32 v[50:51], v[18:19]
	v_mov_b64_e32 v[46:47], v[30:31]
	v_mov_b64_e32 v[44:45], v[28:29]
	v_mov_b64_e32 v[42:43], v[26:27]
	v_mov_b64_e32 v[40:41], v[24:25]
	v_mov_b64_e32 v[38:39], v[22:23]
	v_mov_b64_e32 v[36:37], v[20:21]
	v_mov_b64_e32 v[34:35], v[18:19]
	v_mov_b64_e32 v[4:5], v[20:21]
	v_mov_b64_e32 v[6:7], v[22:23]
	v_mov_b64_e32 v[8:9], v[24:25]
	v_mov_b64_e32 v[10:11], v[26:27]
	v_mov_b64_e32 v[12:13], v[28:29]
	v_mov_b64_e32 v[14:15], v[30:31]
	v_mov_b64_e32 v[16:17], v[32:33]
	s_mov_b32 s8, 1
	v_xor_b32_e32 v220, 0x80000000, v210
	v_mov_b32_e32 v221, v220
	v_mov_b32_e32 v222, v220
	v_mov_b32_e32 v223, v220
	v_mov_b32_e32 v224, v220
	v_mov_b32_e32 v225, v220
	v_mov_b32_e32 v226, v220
	v_mov_b32_e32 v227, v220
	v_mov_b32_e32 v228, v220
	v_mov_b32_e32 v229, v220
	v_mov_b32_e32 v230, v220
	v_mov_b32_e32 v231, v220
	v_mov_b32_e32 v232, v220
	v_mov_b32_e32 v233, v220
	v_mov_b32_e32 v234, v220
	v_mov_b32_e32 v235, v220

.LBB0_445:
	s_mul_i32 s14, s8, 0x7400
	v_add_u32_e32 v0, s14, v208
	ds_read_b128 v[126:129], v0
	ds_read_b128 v[130:133], v0 offset:4608
	ds_read_b128 v[134:137], v0 offset:32
	s_waitcnt lgkmcnt(2)
	v_mfma_f32_32x32x16_bf16 v[82:97], v[126:129], v[98:101], v[220:235]
	v_add_f32_e64 v126, v158, 0
	v_add_f32_e64 v127, v159, 0
	v_cvt_pk_bf16_f32 v138, v158, v159
	v_add_f32_e64 v140, v160, v126
	v_add_f32_e64 v141, v161, v127
	v_cvt_pk_bf16_f32 v139, v160, v161
	s_waitcnt lgkmcnt(1)
	v_mfma_f32_32x32x16_bf16 v[66:81], v[130:133], v[98:101], v[220:235]
	ds_read_b128 v[126:129], v0 offset:4640
	v_add_f32_e64 v130, v162, v140
	v_add_f32_e64 v131, v163, v141
	v_cvt_pk_bf16_f32 v140, v162, v163
	v_add_f32_e64 v158, v164, v130
	v_add_f32_e64 v159, v165, v131
	v_cvt_pk_bf16_f32 v141, v164, v165
	s_waitcnt lgkmcnt(1)
	v_mfma_f32_32x32x16_bf16 v[82:97], v[134:137], v[102:105], v[82:97]
	ds_read_b128 v[130:133], v0 offset:64
	v_add_f32_e64 v136, v166, v158
	v_add_f32_e64 v137, v167, v159
	v_cvt_pk_bf16_f32 v134, v166, v167
	v_add_f32_e64 v136, v170, v136
	v_add_f32_e64 v137, v171, v137
	v_cvt_pk_bf16_f32 v135, v170, v171
	s_waitcnt lgkmcnt(1)
	v_mfma_f32_32x32x16_bf16 v[66:81], v[126:129], v[102:105], v[66:81]
	ds_read_b128 v[158:161], v0 offset:4672
	v_add_f32_e64 v126, v174, v136
	v_add_f32_e64 v127, v175, v137
	v_cvt_pk_bf16_f32 v136, v174, v175
	v_add_f32_e64 v162, v178, v126
	v_add_f32_e64 v163, v179, v127
	v_cvt_pk_bf16_f32 v137, v178, v179
	s_waitcnt lgkmcnt(1)
	v_mfma_f32_32x32x16_bf16 v[82:97], v[130:133], v[106:109], v[82:97]
	ds_read_b128 v[126:129], v0 offset:96
	v_add_f32_e64 v132, v168, v162
	v_add_f32_e64 v133, v169, v163
	v_cvt_pk_bf16_f32 v130, v168, v169
	v_add_f32_e64 v132, v172, v132
	v_add_f32_e64 v133, v173, v133
	v_cvt_pk_bf16_f32 v131, v172, v173
	s_waitcnt lgkmcnt(1)
	v_mfma_f32_32x32x16_bf16 v[66:81], v[158:161], v[106:109], v[66:81]
	ds_read_b128 v[162:165], v0 offset:4704
	v_add_f32_e64 v158, v176, v132
	v_add_f32_e64 v159, v177, v133
	v_cvt_pk_bf16_f32 v132, v176, v177
	v_add_f32_e64 v158, v180, v158
	v_add_f32_e64 v159, v181, v159
	v_cvt_pk_bf16_f32 v133, v180, v181
	s_waitcnt lgkmcnt(1)
	v_mfma_f32_32x32x16_bf16 v[82:97], v[126:129], v[110:113], v[82:97]
	v_add_f32_e64 v128, v182, v158
	v_add_f32_e64 v129, v183, v159
	v_cvt_pk_bf16_f32 v126, v182, v183
	v_add_f32_e64 v128, v184, v128
	v_add_f32_e64 v129, v185, v129
	v_cvt_pk_bf16_f32 v127, v184, v185
	s_waitcnt lgkmcnt(0)
	v_mfma_f32_32x32x16_bf16 v[66:81], v[162:165], v[110:113], v[66:81]
	v_add_f32_e64 v158, v186, v128
	v_add_f32_e64 v159, v187, v129
	v_cvt_pk_bf16_f32 v128, v186, v187
	v_add_f32_e64 v158, v188, v158
	v_add_f32_e64 v159, v189, v159
	v_cvt_pk_bf16_f32 v129, v188, v189
	s_nop 0
	v_add_f32_e32 v0, v158, v159
	v_max_f32_e32 v158, v83, v83
	v_max_f32_e32 v159, v82, v82
	v_max_f32_e32 v158, v159, v158
	v_max3_f32 v158, v158, v84, v85
	v_max3_f32 v158, v158, v86, v87
	v_max3_f32 v158, v158, v88, v89
	v_max3_f32 v158, v158, v90, v91
	v_max3_f32 v158, v158, v92, v93
	v_max3_f32 v158, v158, v94, v95
	v_max3_f32 v158, v158, v96, v97
	v_max3_f32 v158, v158, v66, v67
	v_max3_f32 v158, v158, v68, v69
	v_max3_f32 v158, v158, v70, v71
	v_max3_f32 v158, v158, v72, v73
	v_max3_f32 v158, v158, v74, v75
	v_max3_f32 v158, v158, v76, v77
	v_max3_f32 v158, v158, v78, v79
	v_max3_f32 v158, v158, v80, v81
	v_add_f32_e32 v206, v206, v0
	ds_bpermute_b32 v0, v190, v158
	s_waitcnt lgkmcnt(0)
	v_max_f32_e32 v0, v0, v0
	v_max_f32_e32 v0, v158, v0
	v_cmp_lt_f32_e32 vcc, s30, v0
	s_cmp_lg_u64 vcc, 0
	s_cselect_b64 s[12:13], -1, 0
	s_cbranch_vccz .LBB0_447
	v_max_f32_e32 v0, v0, v0
	v_max_f32_e32 v158, 0, v0
	v_exp_f32_e64 v0, -v158
	v_add_f32_e32 v210, v210, v158
	v_xor_b32_e32 v220, 0x80000000, v210
	v_mov_b32_e32 v221, v220
	v_mov_b32_e32 v222, v220
	v_mov_b32_e32 v223, v220
	v_mov_b32_e32 v224, v220
	v_mov_b32_e32 v225, v220
	v_mov_b32_e32 v226, v220
	v_mov_b32_e32 v227, v220
	v_mov_b32_e32 v228, v220
	v_mov_b32_e32 v229, v220
	v_mov_b32_e32 v230, v220
	v_mov_b32_e32 v231, v220
	v_mov_b32_e32 v232, v220
	v_mov_b32_e32 v233, v220
	v_mov_b32_e32 v234, v220
	v_mov_b32_e32 v235, v220
	v_pk_add_f32 v[82:83], v[82:83], v[158:159] op_sel_hi:[1,0] neg_lo:[0,1] neg_hi:[0,1]
	v_pk_add_f32 v[66:67], v[66:67], v[158:159] op_sel_hi:[1,0] neg_lo:[0,1] neg_hi:[0,1]
	v_pk_add_f32 v[84:85], v[84:85], v[158:159] op_sel_hi:[1,0] neg_lo:[0,1] neg_hi:[0,1]
	v_pk_add_f32 v[68:69], v[68:69], v[158:159] op_sel_hi:[1,0] neg_lo:[0,1] neg_hi:[0,1]
	v_pk_add_f32 v[86:87], v[86:87], v[158:159] op_sel_hi:[1,0] neg_lo:[0,1] neg_hi:[0,1]
	v_pk_add_f32 v[70:71], v[70:71], v[158:159] op_sel_hi:[1,0] neg_lo:[0,1] neg_hi:[0,1]
	v_pk_add_f32 v[88:89], v[88:89], v[158:159] op_sel_hi:[1,0] neg_lo:[0,1] neg_hi:[0,1]
	v_pk_add_f32 v[72:73], v[72:73], v[158:159] op_sel_hi:[1,0] neg_lo:[0,1] neg_hi:[0,1]
	v_pk_add_f32 v[90:91], v[90:91], v[158:159] op_sel_hi:[1,0] neg_lo:[0,1] neg_hi:[0,1]
	v_pk_add_f32 v[74:75], v[74:75], v[158:159] op_sel_hi:[1,0] neg_lo:[0,1] neg_hi:[0,1]
	v_pk_add_f32 v[92:93], v[92:93], v[158:159] op_sel_hi:[1,0] neg_lo:[0,1] neg_hi:[0,1]
	v_pk_add_f32 v[76:77], v[76:77], v[158:159] op_sel_hi:[1,0] neg_lo:[0,1] neg_hi:[0,1]
	v_pk_add_f32 v[94:95], v[94:95], v[158:159] op_sel_hi:[1,0] neg_lo:[0,1] neg_hi:[0,1]
	v_pk_add_f32 v[78:79], v[78:79], v[158:159] op_sel_hi:[1,0] neg_lo:[0,1] neg_hi:[0,1]
	v_pk_add_f32 v[96:97], v[96:97], v[158:159] op_sel_hi:[1,0] neg_lo:[0,1] neg_hi:[0,1]
	v_pk_add_f32 v[80:81], v[80:81], v[158:159] op_sel_hi:[1,0] neg_lo:[0,1] neg_hi:[0,1]
	v_mul_f32_e32 v206, v206, v0
	s_branch .LBB0_448

.LBB0_454:
	v_add_u32_e32 v0, s14, v211
	ds_read_b128 v[70:73], v0 offset:9216
	ds_read_b128 v[74:77], v0 offset:9248
	v_cvt_pk_bf16_f32 v66, v158, v159
	v_cvt_pk_bf16_f32 v67, v160, v161
	v_cvt_pk_bf16_f32 v68, v162, v163
	v_cvt_pk_bf16_f32 v69, v164, v165
	s_movk_i32 s28, 0x50
	s_movk_i32 s8, 0x2000
	s_waitcnt lgkmcnt(1)
	v_mfma_f32_32x32x16_bf16 v[18:33], v[70:73], v[66:69], v[18:33]
	ds_read_b128 v[70:73], v0 offset:11776
	s_mov_b32 s12, s9
	s_mov_b32 s13, s9
	s_mov_b32 s14, s9
	s_mov_b32 s15, s9
	s_mov_b32 s16, s9
	s_mov_b32 s17, s9
	s_waitcnt lgkmcnt(0)
	v_mfma_f32_32x32x16_bf16 v[50:65], v[70:73], v[66:69], v[50:65]
	ds_read_b128 v[70:73], v0 offset:14336
	s_mov_b32 s18, s9
	s_mov_b32 s19, s9
	s_mov_b32 s20, s9
	s_mov_b32 s21, s9
	s_mov_b32 s22, s9
	s_mov_b32 s23, s9
	s_waitcnt lgkmcnt(0)
	v_mfma_f32_32x32x16_bf16 v[34:49], v[70:73], v[66:69], v[34:49]
	ds_read_b128 v[70:73], v0 offset:16896
	s_mov_b32 s25, 1
	s_mov_b32 s24, 0
	s_waitcnt lgkmcnt(0)
	v_mfma_f32_32x32x16_bf16 v[2:17], v[70:73], v[66:69], v[2:17]
	ds_read_b128 v[70:73], v0 offset:11808
	v_cvt_pk_bf16_f32 v66, v166, v167
	v_cvt_pk_bf16_f32 v67, v170, v171
	v_cvt_pk_bf16_f32 v68, v174, v175
	v_cvt_pk_bf16_f32 v69, v178, v179
	s_waitcnt lgkmcnt(0)
	s_nop 0
	v_mfma_f32_32x32x16_bf16 v[50:65], v[70:73], v[66:69], v[50:65]
	ds_read_b128 v[70:73], v0 offset:14368
	s_waitcnt lgkmcnt(0)
	v_mfma_f32_32x32x16_bf16 v[34:49], v[70:73], v[66:69], v[34:49]
	ds_read_b128 v[70:73], v0 offset:16928
	s_waitcnt lgkmcnt(0)
	v_mfma_f32_32x32x16_bf16 v[2:17], v[70:73], v[66:69], v[2:17]
	ds_read_b128 v[70:73], v0 offset:19456
	v_mfma_f32_32x32x16_bf16 v[18:33], v[74:77], v[66:69], v[18:33]
	v_cvt_pk_bf16_f32 v66, v168, v169
	v_cvt_pk_bf16_f32 v67, v172, v173
	v_cvt_pk_bf16_f32 v68, v176, v177
	v_cvt_pk_bf16_f32 v69, v180, v181
	s_waitcnt lgkmcnt(0)
	s_nop 0
	v_mfma_f32_32x32x16_bf16 v[18:33], v[70:73], v[66:69], v[18:33]
	ds_read_b128 v[70:73], v0 offset:22016
	s_waitcnt lgkmcnt(0)
	v_mfma_f32_32x32x16_bf16 v[50:65], v[70:73], v[66:69], v[50:65]
	ds_read_b128 v[70:73], v0 offset:24576
	s_waitcnt lgkmcnt(0)
	v_mfma_f32_32x32x16_bf16 v[34:49], v[70:73], v[66:69], v[34:49]
	ds_read_b128 v[70:73], v0 offset:27136
	s_waitcnt lgkmcnt(0)
	v_mfma_f32_32x32x16_bf16 v[2:17], v[70:73], v[66:69], v[2:17]
	ds_read_b128 v[70:73], v0 offset:19488
	v_cvt_pk_bf16_f32 v66, v182, v183
	v_cvt_pk_bf16_f32 v67, v184, v185
	v_cvt_pk_bf16_f32 v68, v186, v187
	v_cvt_pk_bf16_f32 v69, v188, v189
	s_waitcnt lgkmcnt(0)
	s_nop 0
	v_mfma_f32_32x32x16_bf16 v[18:33], v[70:73], v[66:69], v[18:33]
	ds_read_b128 v[70:73], v0 offset:22048
	s_waitcnt lgkmcnt(0)
	v_mfma_f32_32x32x16_bf16 v[50:65], v[70:73], v[66:69], v[50:65]
	ds_read_b128 v[70:73], v0 offset:24608
	s_waitcnt lgkmcnt(0)
	v_mfma_f32_32x32x16_bf16 v[34:49], v[70:73], v[66:69], v[34:49]
	ds_read_b128 v[70:73], v0 offset:27168
	v_add_f32_e32 v0, 0, v158
	v_add_f32_e32 v0, v0, v159
	v_add_f32_e32 v0, v0, v160
	v_add_f32_e32 v0, v0, v161
	v_add_f32_e32 v0, v0, v162
	v_add_f32_e32 v0, v0, v163
	v_add_f32_e32 v0, v0, v164
	v_add_f32_e32 v0, v0, v165
	v_add_f32_e32 v0, v0, v166
	v_add_f32_e32 v0, v0, v167
	v_add_f32_e32 v0, v0, v170
	v_add_f32_e32 v0, v0, v171
	v_add_f32_e32 v0, v0, v174
	v_add_f32_e32 v0, v0, v175
	v_add_f32_e32 v0, v0, v178
	v_add_f32_e32 v0, v0, v179
	v_add_f32_e32 v0, v0, v168
	v_add_f32_e32 v0, v0, v169
	v_add_f32_e32 v0, v0, v172
	v_add_f32_e32 v0, v0, v173
	v_add_f32_e32 v0, v0, v176
	v_add_f32_e32 v0, v0, v177
	v_add_f32_e32 v0, v0, v180
	v_add_f32_e32 v0, v0, v181
	v_add_f32_e32 v0, v0, v182
	v_add_f32_e32 v0, v0, v183
	v_add_f32_e32 v0, v0, v184
	v_add_f32_e32 v0, v0, v185
	v_add_f32_e32 v0, v0, v186
	v_add_f32_e32 v0, v0, v187
	v_add_f32_e32 v0, v0, v188
	v_add_f32_e32 v0, v0, v189
	v_add_f32_e32 v0, v206, v0
	s_waitcnt lgkmcnt(0)
	v_mfma_f32_32x32x16_bf16 v[2:17], v[70:73], v[66:69], v[2:17]
	ds_bpermute_b32 v66, v190, v0
	s_waitcnt lgkmcnt(0)
	v_add_f32_e32 v0, v0, v66
	v_div_scale_f32 v66, s[10:11], v0, v0, 1.0
	v_rcp_f32_e32 v67, v66
	s_mov_b32 s10, 0x20000
	s_mov_b32 s11, s9
	v_fma_f32 v68, -v66, v67, 1.0
	v_fmac_f32_e32 v67, v68, v67
	v_div_scale_f32 v68, vcc, 1.0, v0, 1.0
	v_mul_f32_e32 v69, v68, v67
	v_fma_f32 v70, -v66, v69, v68
	v_fmac_f32_e32 v69, v70, v67
	v_fma_f32 v66, -v66, v69, v68
	v_div_fmas_f32 v66, v66, v67, v69
	v_div_fixup_f32 v0, v66, v0, 1.0
	v_pk_mul_f32 v[18:19], v[18:19], v[0:1] op_sel_hi:[1,0]
	v_lshl_add_u32 v67, v151, 2, v192
	v_cvt_pk_bf16_f32 v66, v18, v19
	v_pk_mul_f32 v[18:19], v[20:21], v[0:1] op_sel_hi:[1,0]
	v_pk_mul_f32 v[2:3], v[2:3], v[0:1] op_sel_hi:[1,0]
	v_cvt_pk_bf16_f32 v18, v18, v19
	ds_write2st64_b32 v67, v66, v18 offset1:1
	v_pk_mul_f32 v[18:19], v[22:23], v[0:1] op_sel_hi:[1,0]
	v_mov_b32_e32 v151, v1
	v_cvt_pk_bf16_f32 v20, v18, v19
	v_pk_mul_f32 v[18:19], v[24:25], v[0:1] op_sel_hi:[1,0]
	s_nop 0
	v_cvt_pk_bf16_f32 v18, v18, v19
	ds_write2st64_b32 v67, v20, v18 offset0:2 offset1:3
	v_pk_mul_f32 v[18:19], v[26:27], v[0:1] op_sel_hi:[1,0]
	s_nop 0
	v_cvt_pk_bf16_f32 v20, v18, v19
	v_pk_mul_f32 v[18:19], v[28:29], v[0:1] op_sel_hi:[1,0]
	s_nop 0
	v_cvt_pk_bf16_f32 v18, v18, v19
	ds_write2st64_b32 v67, v20, v18 offset0:4 offset1:5
	v_pk_mul_f32 v[18:19], v[30:31], v[0:1] op_sel_hi:[1,0]
	s_nop 0
	v_cvt_pk_bf16_f32 v20, v18, v19
	v_pk_mul_f32 v[18:19], v[32:33], v[0:1] op_sel_hi:[1,0]
	s_nop 0
	v_cvt_pk_bf16_f32 v18, v18, v19
	ds_write2st64_b32 v67, v20, v18 offset0:6 offset1:7
	v_pk_mul_f32 v[18:19], v[50:51], v[0:1] op_sel_hi:[1,0]
	s_nop 0
	v_cvt_pk_bf16_f32 v20, v18, v19
	v_pk_mul_f32 v[18:19], v[52:53], v[0:1] op_sel_hi:[1,0]
	s_nop 0
	v_cvt_pk_bf16_f32 v18, v18, v19
	ds_write2st64_b32 v67, v20, v18 offset0:8 offset1:9
	v_pk_mul_f32 v[18:19], v[54:55], v[0:1] op_sel_hi:[1,0]
	s_nop 0
	v_cvt_pk_bf16_f32 v20, v18, v19
	v_pk_mul_f32 v[18:19], v[56:57], v[0:1] op_sel_hi:[1,0]
	s_nop 0
	v_cvt_pk_bf16_f32 v18, v18, v19
	ds_write2st64_b32 v67, v20, v18 offset0:10 offset1:11
	v_pk_mul_f32 v[18:19], v[58:59], v[0:1] op_sel_hi:[1,0]
	s_nop 0
	v_cvt_pk_bf16_f32 v20, v18, v19
	v_pk_mul_f32 v[18:19], v[60:61], v[0:1] op_sel_hi:[1,0]
	s_nop 0
	v_cvt_pk_bf16_f32 v18, v18, v19
	ds_write2st64_b32 v67, v20, v18 offset0:12 offset1:13
	v_pk_mul_f32 v[18:19], v[62:63], v[0:1] op_sel_hi:[1,0]
	s_nop 0
	v_cvt_pk_bf16_f32 v20, v18, v19
	v_pk_mul_f32 v[18:19], v[64:65], v[0:1] op_sel_hi:[1,0]
	s_nop 0
	v_cvt_pk_bf16_f32 v18, v18, v19
	ds_write2st64_b32 v67, v20, v18 offset0:14 offset1:15
	v_pk_mul_f32 v[18:19], v[34:35], v[0:1] op_sel_hi:[1,0]
	s_nop 0
	v_cvt_pk_bf16_f32 v20, v18, v19
	v_pk_mul_f32 v[18:19], v[36:37], v[0:1] op_sel_hi:[1,0]
	s_nop 0
	v_cvt_pk_bf16_f32 v18, v18, v19
	ds_write2st64_b32 v67, v20, v18 offset0:16 offset1:17
	v_pk_mul_f32 v[18:19], v[38:39], v[0:1] op_sel_hi:[1,0]
	s_nop 0
	v_cvt_pk_bf16_f32 v20, v18, v19
	v_pk_mul_f32 v[18:19], v[40:41], v[0:1] op_sel_hi:[1,0]
	s_nop 0
	v_cvt_pk_bf16_f32 v18, v18, v19
	ds_write2st64_b32 v67, v20, v18 offset0:18 offset1:19
	v_pk_mul_f32 v[18:19], v[42:43], v[0:1] op_sel_hi:[1,0]
	s_nop 0
	v_cvt_pk_bf16_f32 v20, v18, v19
	v_pk_mul_f32 v[18:19], v[44:45], v[0:1] op_sel_hi:[1,0]
	s_nop 0
	v_cvt_pk_bf16_f32 v18, v18, v19
	ds_write2st64_b32 v67, v20, v18 offset0:20 offset1:21
	v_pk_mul_f32 v[18:19], v[46:47], v[0:1] op_sel_hi:[1,0]
	s_nop 0
	v_cvt_pk_bf16_f32 v20, v18, v19
	v_pk_mul_f32 v[18:19], v[48:49], v[0:1] op_sel_hi:[1,0]
	s_nop 0
	v_cvt_pk_bf16_f32 v18, v18, v19
	ds_write2st64_b32 v67, v20, v18 offset0:22 offset1:23
	v_cvt_pk_bf16_f32 v18, v2, v3
	v_pk_mul_f32 v[2:3], v[4:5], v[0:1] op_sel_hi:[1,0]
	s_nop 0
	v_cvt_pk_bf16_f32 v2, v2, v3
	ds_write2st64_b32 v67, v18, v2 offset0:24 offset1:25
	v_pk_mul_f32 v[2:3], v[6:7], v[0:1] op_sel_hi:[1,0]
	s_nop 0
	v_cvt_pk_bf16_f32 v4, v2, v3
	v_pk_mul_f32 v[2:3], v[8:9], v[0:1] op_sel_hi:[1,0]
	s_nop 0
	v_cvt_pk_bf16_f32 v2, v2, v3
	ds_write2st64_b32 v67, v4, v2 offset0:26 offset1:27
	v_pk_mul_f32 v[2:3], v[10:11], v[0:1] op_sel_hi:[1,0]
	s_nop 0
	v_cvt_pk_bf16_f32 v4, v2, v3
	v_pk_mul_f32 v[2:3], v[12:13], v[0:1] op_sel_hi:[1,0]
	s_nop 0
	v_cvt_pk_bf16_f32 v2, v2, v3
	ds_write2st64_b32 v67, v4, v2 offset0:28 offset1:29
	v_pk_mul_f32 v[2:3], v[14:15], v[0:1] op_sel_hi:[1,0]
	s_nop 0
	v_cvt_pk_bf16_f32 v4, v2, v3
	v_pk_mul_f32 v[2:3], v[16:17], v[0:1] op_sel_hi:[1,0]
	s_nop 0
	v_cvt_pk_bf16_f32 v0, v2, v3
	ds_write2st64_b32 v67, v4, v0 offset0:30 offset1:31
	v_mov_b32_e32 v0, v147
	s_nop 0
	v_bfe_u32 v189, v0, 5, 1
	v_lshlrev_b32_e32 v2, 1, v0
	v_and_b32_e32 v16, 8, v2
	v_lshrrev_b32_e32 v2, 1, v0
	v_lshlrev_b32_e32 v150, 4, v189
	v_and_b32_e32 v17, 4, v2
	v_lshl_add_u64 v[2:3], v[152:153], 0, v[150:151]
	global_load_dwordx4 v[98:101], v[2:3], off offset:128
	global_load_dwordx4 v[102:105], v[2:3], off offset:160
	global_load_dwordx4 v[106:109], v[2:3], off offset:192
	global_load_dwordx4 v[110:113], v[2:3], off offset:224
	v_ashrrev_i32_e32 v2, 31, v0
	v_lshrrev_b32_e32 v2, 23, v2
	v_add_u32_e32 v2, v0, v2
	v_ashrrev_i32_e32 v3, 9, v2
	v_and_b32_e32 v2, 0xfffffe00, v2
	v_ashrrev_i32_e32 v10, 3, v0
	v_sub_u32_e32 v2, v0, v2
	v_lshlrev_b32_e32 v4, 12, v3
	v_ashrrev_i32_e32 v2, 2, v2
	v_ashrrev_i32_e32 v11, 31, v10
	v_and_b32_e32 v206, 63, v0
	v_and_b32_e32 v18, 19, v0
	v_and_b32_e32 v19, 3, v0
	v_and_b32_e32 v54, 31, v0
	v_lshl_add_u32 v4, v2, 5, v4
	v_lshl_add_u32 v2, v3, 7, v2
	v_lshlrev_b64 v[52:53], 11, v[10:11]
	v_lshlrev_b32_e32 v0, 4, v0
	v_mul_lo_u32 v20, v2, s28
	v_lshl_add_u64 v[2:3], s[40:41], 0, v[52:53]
	v_and_b32_e32 v0, 0x70, v0
	v_lshl_add_u64 v[12:13], v[2:3], 0, v[0:1]
	v_lshl_or_b32 v6, v19, 3, v4
	s_waitcnt lgkmcnt(0)
	s_barrier
	global_load_dwordx4 v[2:5], v[12:13], off offset:128
	v_ashrrev_i32_e32 v7, 31, v6
	v_lshlrev_b64 v[50:51], 1, v[6:7]
	v_mul_lo_u32 v151, v10, s76
	v_lshl_add_u64 v[14:15], s[38:39], 0, v[50:51]
	v_add_u32_e32 v55, v151, v0
	global_load_dwordx4 v[6:9], v[14:15], off
	v_lshl_add_u32 v207, v19, 4, v20
	v_mad_u32_u24 v211, v54, s28, v150
	s_waitcnt vmcnt(1)
	ds_write_b128 v55, v[2:5]
	v_add_co_u32_e32 v2, vcc, s8, v14
	s_nop 1
	v_addc_co_u32_e32 v3, vcc, 0, v15, vcc
	global_load_dwordx4 v[2:5], v[2:3], off
	s_waitcnt vmcnt(1)
	ds_write_b128 v207, v[6:9] offset:9216
	s_waitcnt vmcnt(0)
	ds_write_b128 v207, v[2:5] offset:19456
	v_add_co_u32_e32 v2, vcc, s10, v12
	s_waitcnt lgkmcnt(0)
	s_nop 0
	v_addc_co_u32_e32 v3, vcc, 0, v13, vcc
	s_barrier
	global_load_dwordx4 v[114:117], v[2:3], off offset:128
	v_lshl_add_u64 v[2:3], s[42:43], 0, v[50:51]
	global_load_dwordx4 v[118:121], v[2:3], off
	v_add_co_u32_e32 v2, vcc, s8, v2
	s_mov_b32 s8, s9
	s_nop 0
	v_addc_co_u32_e32 v3, vcc, 0, v3, vcc
	global_load_dwordx4 v[122:125], v[2:3], off
	v_or3_b32 v2, v18, v16, v17
	v_mad_u32_u24 v208, v2, s76, v150
	ds_read_b128 v[34:37], v208 offset:4608
	ds_read_b128 v[18:21], v208
	ds_read_b128 v[38:41], v208 offset:32
	s_waitcnt lgkmcnt(1)
	v_mfma_f32_32x32x16_bf16 v[18:33], v[18:21], v[98:101], 0
	ds_read_b128 v[56:59], v208 offset:4640
	s_mov_b32 s10, s9
	v_mov_b64_e32 v[2:3], s[8:9]
	v_mov_b64_e32 v[4:5], s[10:11]
	v_mov_b64_e32 v[6:7], s[12:13]
	v_mov_b64_e32 v[8:9], s[14:15]
	v_mov_b64_e32 v[10:11], s[16:17]
	s_waitcnt lgkmcnt(1)
	v_mfma_f32_32x32x16_bf16 v[18:33], v[38:41], v[102:105], v[18:33]
	ds_read_b128 v[38:41], v208 offset:64
	ds_read_b128 v[60:63], v208 offset:4672
	v_mov_b64_e32 v[12:13], s[18:19]
	v_mov_b64_e32 v[14:15], s[20:21]
	v_mov_b64_e32 v[16:17], s[22:23]
	s_mov_b32 s8, 0xf149f2ca
	s_waitcnt lgkmcnt(1)
	v_mfma_f32_32x32x16_bf16 v[18:33], v[38:41], v[106:109], v[18:33]
	ds_read_b128 v[38:41], v208 offset:96
	ds_read_b128 v[64:67], v208 offset:4704
	s_waitcnt vmcnt(2)
	ds_write_b128 v55, v[114:117] offset:29696
	s_waitcnt vmcnt(1)
	ds_write_b128 v207, v[118:121] offset:38912
	s_waitcnt vmcnt(0)
	ds_write_b128 v207, v[122:125] offset:49152
	s_waitcnt lgkmcnt(4)
	v_mfma_f32_32x32x16_bf16 v[18:33], v[38:41], v[110:113], v[18:33]
	s_waitcnt lgkmcnt(0)
	s_barrier
	s_nop 9
	v_max_f32_e32 v38, v19, v19
	v_max_f32_e32 v39, v18, v18
	v_max_f32_e32 v38, v39, v38
	v_max3_f32 v38, v38, v20, v21
	v_max3_f32 v38, v38, v22, v23
	v_max3_f32 v38, v38, v24, v25
	v_max3_f32 v38, v38, v26, v27
	v_max3_f32 v38, v38, v28, v29
	v_max3_f32 v38, v38, v30, v31
	v_max3_f32 v68, v38, v32, v33
	v_mfma_f32_32x32x16_bf16 v[34:49], v[34:37], v[98:101], 0
	v_mfma_f32_32x32x16_bf16 v[34:49], v[56:59], v[102:105], v[34:49]
	v_mfma_f32_32x32x16_bf16 v[34:49], v[60:63], v[106:109], v[34:49]
	v_mfma_f32_32x32x16_bf16 v[34:49], v[64:67], v[110:113], v[34:49]
	s_nop 11
	v_max3_f32 v56, v68, v34, v35
	v_max3_f32 v56, v56, v36, v37
	v_max3_f32 v56, v56, v38, v39
	v_max3_f32 v56, v56, v40, v41
	v_max3_f32 v56, v56, v42, v43
	v_max3_f32 v56, v56, v44, v45
	v_max3_f32 v56, v56, v46, v47
	v_max3_f32 v56, v56, v48, v49
	ds_bpermute_b32 v57, v190, v56
	s_waitcnt lgkmcnt(0)
	v_max3_f32 v210, v56, v57, s8
	v_sub_f32_e32 v18, v18, v210
	v_exp_f32_e32 v156, v18
	v_sub_f32_e32 v18, v34, v210
	v_exp_f32_e32 v166, v18
	v_sub_f32_e32 v18, v19, v210
	v_exp_f32_e32 v157, v18
	v_sub_f32_e32 v18, v35, v210
	v_exp_f32_e32 v167, v18
	v_sub_f32_e32 v18, v20, v210
	v_exp_f32_e32 v158, v18
	v_sub_f32_e32 v18, v36, v210
	v_exp_f32_e32 v170, v18
	v_sub_f32_e32 v18, v21, v210
	v_exp_f32_e32 v159, v18
	v_sub_f32_e32 v18, v37, v210
	v_exp_f32_e32 v171, v18
	v_sub_f32_e32 v18, v22, v210
	v_exp_f32_e32 v160, v18
	v_sub_f32_e32 v18, v38, v210
	v_exp_f32_e32 v174, v18
	v_sub_f32_e32 v18, v23, v210
	v_exp_f32_e32 v161, v18
	v_sub_f32_e32 v18, v39, v210
	v_exp_f32_e32 v175, v18
	v_sub_f32_e32 v18, v24, v210
	v_exp_f32_e32 v162, v18
	v_sub_f32_e32 v18, v40, v210
	v_exp_f32_e32 v178, v18
	v_sub_f32_e32 v18, v25, v210
	v_exp_f32_e32 v163, v18
	v_sub_f32_e32 v18, v41, v210
	v_exp_f32_e32 v179, v18
	v_sub_f32_e32 v18, v26, v210
	v_exp_f32_e32 v164, v18
	v_sub_f32_e32 v18, v42, v210
	v_exp_f32_e32 v180, v18
	v_sub_f32_e32 v18, v27, v210
	v_exp_f32_e32 v165, v18
	v_sub_f32_e32 v18, v43, v210
	v_exp_f32_e32 v181, v18
	v_sub_f32_e32 v18, v28, v210
	v_exp_f32_e32 v168, v18
	v_sub_f32_e32 v18, v44, v210
	v_exp_f32_e32 v182, v18
	v_sub_f32_e32 v18, v29, v210
	v_exp_f32_e32 v169, v18
	v_sub_f32_e32 v18, v45, v210
	v_exp_f32_e32 v183, v18
	v_sub_f32_e32 v18, v30, v210
	v_exp_f32_e32 v172, v18
	v_sub_f32_e32 v18, v46, v210
	v_exp_f32_e32 v184, v18
	v_sub_f32_e32 v18, v31, v210
	v_exp_f32_e32 v173, v18
	v_sub_f32_e32 v18, v47, v210
	v_exp_f32_e32 v185, v18
	v_sub_f32_e32 v18, v32, v210
	v_exp_f32_e32 v176, v18
	v_sub_f32_e32 v18, v48, v210
	v_exp_f32_e32 v186, v18
	v_sub_f32_e32 v18, v33, v210
	v_exp_f32_e32 v177, v18
	v_sub_f32_e32 v18, v49, v210
	v_exp_f32_e32 v187, v18
	v_lshl_add_u64 v[18:19], s[6:7], 0, v[52:53]
	v_readlane_b32 s6, v242, 55
	v_sub_f32_e32 v56, 0xf149f2ca, v210
	s_add_u32 s4, s6, s4
	v_readlane_b32 s6, v242, 56
	v_exp_f32_e32 v56, v56
	v_lshl_add_u64 v[18:19], v[18:19], 0, v[0:1]
	s_addc_u32 s5, s6, s5
	v_lshl_add_u64 v[152:153], s[4:5], 0, v[18:19]
	v_readlane_b32 s4, v242, 57
	s_add_u32 s4, s4, s36
	v_readlane_b32 s5, v242, 58
	s_addc_u32 s5, s5, s37
	v_mul_f32_e32 v209, 0, v56
	v_lshl_add_u64 v[154:155], s[4:5], 0, v[50:51]
	v_mov_b64_e32 v[64:65], v[16:17]
	v_mov_b64_e32 v[48:49], v[16:17]
	v_mov_b64_e32 v[32:33], v[16:17]
	v_mov_b64_e32 v[62:63], v[14:15]
	v_mov_b64_e32 v[60:61], v[12:13]
	v_mov_b64_e32 v[58:59], v[10:11]
	v_mov_b64_e32 v[56:57], v[8:9]
	v_mov_b64_e32 v[54:55], v[6:7]
	v_mov_b64_e32 v[52:53], v[4:5]
	v_mov_b64_e32 v[50:51], v[2:3]
	v_mov_b64_e32 v[46:47], v[14:15]
	v_mov_b64_e32 v[44:45], v[12:13]
	v_mov_b64_e32 v[42:43], v[10:11]
	v_mov_b64_e32 v[40:41], v[8:9]
	v_mov_b64_e32 v[38:39], v[6:7]
	v_mov_b64_e32 v[36:37], v[4:5]
	v_mov_b64_e32 v[34:35], v[2:3]
	v_mov_b64_e32 v[30:31], v[14:15]
	v_mov_b64_e32 v[28:29], v[12:13]
	v_mov_b64_e32 v[26:27], v[10:11]
	v_mov_b64_e32 v[24:25], v[8:9]
	v_mov_b64_e32 v[22:23], v[6:7]
	v_mov_b64_e32 v[20:21], v[4:5]
	v_mov_b64_e32 v[18:19], v[2:3]
	s_mov_b32 s8, 1
	v_xor_b32_e32 v220, 0x80000000, v210
	v_mov_b32_e32 v221, v220
	v_mov_b32_e32 v222, v220
	v_mov_b32_e32 v223, v220
	v_mov_b32_e32 v224, v220
	v_mov_b32_e32 v225, v220
	v_mov_b32_e32 v226, v220
	v_mov_b32_e32 v227, v220
	v_mov_b32_e32 v228, v220
	v_mov_b32_e32 v229, v220
	v_mov_b32_e32 v230, v220
	v_mov_b32_e32 v231, v220
	v_mov_b32_e32 v232, v220
	v_mov_b32_e32 v233, v220
	v_mov_b32_e32 v234, v220
	v_mov_b32_e32 v235, v220

.LBB0_457:
	s_mul_i32 s11, s10, 0x7400
	v_add_u32_e32 v188, s11, v208
	ds_read_b128 v[126:129], v188
	ds_read_b128 v[130:133], v188 offset:4608
	ds_read_b128 v[134:137], v188 offset:32
	s_waitcnt lgkmcnt(2)
	v_mfma_f32_32x32x16_bf16 v[82:97], v[126:129], v[98:101], v[220:235]
	v_add_f32_e64 v126, v156, 0
	v_add_f32_e64 v127, v157, 0
	v_cvt_pk_bf16_f32 v138, v156, v157
	v_add_f32_e64 v140, v158, v126
	v_add_f32_e64 v141, v159, v127
	v_cvt_pk_bf16_f32 v139, v158, v159
	s_waitcnt lgkmcnt(1)
	v_mfma_f32_32x32x16_bf16 v[66:81], v[130:133], v[98:101], v[220:235]
	ds_read_b128 v[126:129], v188 offset:4640
	v_add_f32_e64 v130, v160, v140
	v_add_f32_e64 v131, v161, v141
	v_cvt_pk_bf16_f32 v140, v160, v161
	v_add_f32_e64 v156, v162, v130
	v_add_f32_e64 v157, v163, v131
	v_cvt_pk_bf16_f32 v141, v162, v163
	s_waitcnt lgkmcnt(1)
	v_mfma_f32_32x32x16_bf16 v[82:97], v[134:137], v[102:105], v[82:97]
	ds_read_b128 v[130:133], v188 offset:64
	v_add_f32_e64 v136, v164, v156
	v_add_f32_e64 v137, v165, v157
	v_cvt_pk_bf16_f32 v134, v164, v165
	v_add_f32_e64 v136, v168, v136
	v_add_f32_e64 v137, v169, v137
	v_cvt_pk_bf16_f32 v135, v168, v169
	s_waitcnt lgkmcnt(1)
	v_mfma_f32_32x32x16_bf16 v[66:81], v[126:129], v[102:105], v[66:81]
	ds_read_b128 v[156:159], v188 offset:4672
	v_add_f32_e64 v126, v172, v136
	v_add_f32_e64 v127, v173, v137
	v_cvt_pk_bf16_f32 v136, v172, v173
	v_add_f32_e64 v160, v176, v126
	v_add_f32_e64 v161, v177, v127
	v_cvt_pk_bf16_f32 v137, v176, v177
	s_waitcnt lgkmcnt(1)
	v_mfma_f32_32x32x16_bf16 v[82:97], v[130:133], v[106:109], v[82:97]
	ds_read_b128 v[126:129], v188 offset:96
	v_add_f32_e64 v132, v166, v160
	v_add_f32_e64 v133, v167, v161
	v_cvt_pk_bf16_f32 v130, v166, v167
	v_add_f32_e64 v132, v170, v132
	v_add_f32_e64 v133, v171, v133
	v_cvt_pk_bf16_f32 v131, v170, v171
	s_waitcnt lgkmcnt(1)
	v_mfma_f32_32x32x16_bf16 v[66:81], v[156:159], v[106:109], v[66:81]
	ds_read_b128 v[160:163], v188 offset:4704
	v_add_f32_e64 v156, v174, v132
	v_add_f32_e64 v157, v175, v133
	v_cvt_pk_bf16_f32 v132, v174, v175
	v_add_f32_e64 v156, v178, v156
	v_add_f32_e64 v157, v179, v157
	v_cvt_pk_bf16_f32 v133, v178, v179
	s_waitcnt lgkmcnt(1)
	v_mfma_f32_32x32x16_bf16 v[82:97], v[126:129], v[110:113], v[82:97]
	v_add_f32_e64 v128, v180, v156
	v_add_f32_e64 v129, v181, v157
	v_cvt_pk_bf16_f32 v126, v180, v181
	v_add_f32_e64 v128, v182, v128
	v_add_f32_e64 v129, v183, v129
	v_cvt_pk_bf16_f32 v127, v182, v183
	s_waitcnt lgkmcnt(0)
	v_mfma_f32_32x32x16_bf16 v[66:81], v[160:163], v[110:113], v[66:81]
	v_add_f32_e64 v156, v184, v128
	v_add_f32_e64 v157, v185, v129
	v_cvt_pk_bf16_f32 v128, v184, v185
	v_add_f32_e64 v156, v186, v156
	v_add_f32_e64 v157, v187, v157
	v_cvt_pk_bf16_f32 v129, v186, v187
	s_nop 0
	v_add_f32_e32 v156, v156, v157
	v_max_f32_e32 v157, v83, v83
	v_max_f32_e32 v158, v82, v82
	v_max_f32_e32 v157, v158, v157
	v_max3_f32 v157, v157, v84, v85
	v_max3_f32 v157, v157, v86, v87
	v_max3_f32 v157, v157, v88, v89
	v_max3_f32 v157, v157, v90, v91
	v_max3_f32 v157, v157, v92, v93
	v_max3_f32 v157, v157, v94, v95
	v_max3_f32 v157, v157, v96, v97
	v_max3_f32 v157, v157, v66, v67
	v_max3_f32 v157, v157, v68, v69
	v_max3_f32 v157, v157, v70, v71
	v_max3_f32 v157, v157, v72, v73
	v_max3_f32 v157, v157, v74, v75
	v_max3_f32 v157, v157, v76, v77
	v_max3_f32 v157, v157, v78, v79
	v_max3_f32 v157, v157, v80, v81
	v_add_f32_e32 v209, v209, v156
	ds_bpermute_b32 v156, v190, v157
	s_waitcnt lgkmcnt(0)
	v_max_f32_e32 v156, v156, v156
	v_max_f32_e32 v156, v157, v156
	v_cmp_lt_f32_e32 vcc, s30, v156
	s_cmp_lg_u64 vcc, 0
	s_cselect_b64 s[6:7], -1, 0
	s_cbranch_vccz .LBB0_459
	v_max_f32_e32 v156, v156, v156
	v_max_f32_e32 v156, 0, v156
	v_exp_f32_e64 v188, -v156
	v_add_f32_e32 v210, v210, v156
	v_xor_b32_e32 v220, 0x80000000, v210
	v_mov_b32_e32 v221, v220
	v_mov_b32_e32 v222, v220
	v_mov_b32_e32 v223, v220
	v_mov_b32_e32 v224, v220
	v_mov_b32_e32 v225, v220
	v_mov_b32_e32 v226, v220
	v_mov_b32_e32 v227, v220
	v_mov_b32_e32 v228, v220
	v_mov_b32_e32 v229, v220
	v_mov_b32_e32 v230, v220
	v_mov_b32_e32 v231, v220
	v_mov_b32_e32 v232, v220
	v_mov_b32_e32 v233, v220
	v_mov_b32_e32 v234, v220
	v_mov_b32_e32 v235, v220
	v_pk_add_f32 v[82:83], v[82:83], v[156:157] op_sel_hi:[1,0] neg_lo:[0,1] neg_hi:[0,1]
	v_pk_add_f32 v[66:67], v[66:67], v[156:157] op_sel_hi:[1,0] neg_lo:[0,1] neg_hi:[0,1]
	v_pk_add_f32 v[84:85], v[84:85], v[156:157] op_sel_hi:[1,0] neg_lo:[0,1] neg_hi:[0,1]
	v_pk_add_f32 v[68:69], v[68:69], v[156:157] op_sel_hi:[1,0] neg_lo:[0,1] neg_hi:[0,1]
	v_pk_add_f32 v[86:87], v[86:87], v[156:157] op_sel_hi:[1,0] neg_lo:[0,1] neg_hi:[0,1]
	v_pk_add_f32 v[70:71], v[70:71], v[156:157] op_sel_hi:[1,0] neg_lo:[0,1] neg_hi:[0,1]
	v_pk_add_f32 v[88:89], v[88:89], v[156:157] op_sel_hi:[1,0] neg_lo:[0,1] neg_hi:[0,1]
	v_pk_add_f32 v[72:73], v[72:73], v[156:157] op_sel_hi:[1,0] neg_lo:[0,1] neg_hi:[0,1]
	v_pk_add_f32 v[90:91], v[90:91], v[156:157] op_sel_hi:[1,0] neg_lo:[0,1] neg_hi:[0,1]
	v_pk_add_f32 v[74:75], v[74:75], v[156:157] op_sel_hi:[1,0] neg_lo:[0,1] neg_hi:[0,1]
	v_pk_add_f32 v[92:93], v[92:93], v[156:157] op_sel_hi:[1,0] neg_lo:[0,1] neg_hi:[0,1]
	v_pk_add_f32 v[76:77], v[76:77], v[156:157] op_sel_hi:[1,0] neg_lo:[0,1] neg_hi:[0,1]
	v_pk_add_f32 v[94:95], v[94:95], v[156:157] op_sel_hi:[1,0] neg_lo:[0,1] neg_hi:[0,1]
	v_pk_add_f32 v[78:79], v[78:79], v[156:157] op_sel_hi:[1,0] neg_lo:[0,1] neg_hi:[0,1]
	v_pk_add_f32 v[96:97], v[96:97], v[156:157] op_sel_hi:[1,0] neg_lo:[0,1] neg_hi:[0,1]
	v_pk_add_f32 v[80:81], v[80:81], v[156:157] op_sel_hi:[1,0] neg_lo:[0,1] neg_hi:[0,1]
	v_mul_f32_e32 v209, v209, v188
	s_branch .LBB0_460
